# attention loops: 8 of 32 v_exp per step moved from the EX block into add-only filler slots of the P.V block (register-liveness checked)
# speedup vs baseline: 1.0103x; 1.0020x over previous
.LBB0_641:
	v_lshl_add_u64 v[178:179], v[174:175], 0, v[170:171]
	s_mov_b32 s24, 0x1894a000
	v_add_co_u32_e32 v52, vcc, s24, v178
	v_lshl_add_u64 v[56:57], v[172:173], 0, v[170:171]
	s_nop 0
	v_addc_co_u32_e32 v53, vcc, 0, v179, vcc
	s_mov_b32 s24, 0x19980000
	v_add_co_u32_e32 v176, vcc, s24, v56
	s_nop 0
	v_addc_co_u32_e32 v177, vcc, 0, v57, vcc
	global_load_dwordx4 v[52:55], v[52:53], off
	s_mul_i32 s26, s25, 0x2400
	global_load_dwordx4 v[56:59], v[176:177], off offset:512
	s_add_i32 s24, s23, -7
	s_add_i32 s27, s26, 0xffffdc00
	s_cmp_lg_u32 s25, 0
	s_cselect_b32 s27, s27, 0x9000
	v_add_u32_e32 v1, s27, v163
	ds_read_b128 v[60:63], v1 offset:36864
	ds_read_b128 v[114:117], v1 offset:36896
	ds_read_b128 v[118:121], v1 offset:41472
	ds_read_b128 v[134:137], v1 offset:41504
	ds_read_b128 v[146:149], v1 offset:36928
	ds_read_b128 v[150:153], v1 offset:36960
	ds_read_b128 v[196:199], v1 offset:41536
	ds_read_b128 v[200:203], v1 offset:41568
	s_setprio 3
	v_cvt_pk_bf16_f32 v204, v102, v103
	v_cvt_pk_bf16_f32 v205, v104, v105
	v_cvt_pk_bf16_f32 v206, v98, v99
	v_cvt_pk_bf16_f32 v207, v100, v101
	s_waitcnt lgkmcnt(7)
	s_nop 0
	v_mfma_f32_32x32x16_bf16 v[18:33], v[60:63], v[204:207], v[18:33]
	v_mov_b32_e32 v1, v102
	v_add_f32_e32 v1, v1, v103
	v_add_f32_e32 v1, v1, v104
	v_add_f32_e32 v1, v1, v105
	v_exp_f32_e32 v195, v86
	v_exp_f32_e32 v208, v77
	s_waitcnt lgkmcnt(5)
	v_mfma_f32_32x32x16_bf16 v[2:17], v[118:121], v[204:207], v[2:17]
	v_cvt_pk_bf16_f32 v60, v194, v187
	v_cvt_pk_bf16_f32 v61, v186, v185
	v_cvt_pk_bf16_f32 v62, v133, v132
	v_cvt_pk_bf16_f32 v63, v131, v130
	v_add_f32_e32 v1, v1, v98
	v_add_f32_e32 v1, v1, v99
	v_add_f32_e32 v1, v1, v100
	v_add_f32_e32 v1, v1, v101
	s_nop 0
	v_mfma_f32_32x32x16_bf16 v[18:33], v[114:117], v[60:63], v[18:33]
	v_add_f32_e32 v1, v1, v194
	v_add_f32_e32 v1, v1, v187
	v_add_f32_e32 v1, v1, v186
	v_add_f32_e32 v1, v1, v185
	v_exp_f32_e32 v185, v82
	v_exp_f32_e32 v186, v83
	s_waitcnt lgkmcnt(4)
	v_mfma_f32_32x32x16_bf16 v[2:17], v[134:137], v[60:63], v[2:17]
	v_cvt_pk_bf16_f32 v98, v129, v128
	v_cvt_pk_bf16_f32 v99, v127, v126
	v_cvt_pk_bf16_f32 v100, v125, v124
	v_cvt_pk_bf16_f32 v101, v123, v122
	v_add_f32_e32 v1, v1, v133
	v_add_f32_e32 v1, v1, v132
	v_add_f32_e32 v1, v1, v131
	v_add_f32_e32 v1, v1, v130
	s_waitcnt lgkmcnt(3)
	v_mfma_f32_32x32x16_bf16 v[18:33], v[146:149], v[98:101], v[18:33]
	v_add_f32_e32 v1, v1, v129
	v_add_f32_e32 v1, v1, v128
	v_add_f32_e32 v1, v1, v127
	v_add_f32_e32 v1, v1, v126
	v_exp_f32_e32 v187, v84
	v_exp_f32_e32 v194, v85
	s_waitcnt lgkmcnt(1)
	v_mfma_f32_32x32x16_bf16 v[2:17], v[196:199], v[98:101], v[2:17]
	v_cvt_pk_bf16_f32 v60, v109, v108
	v_cvt_pk_bf16_f32 v61, v107, v106
	v_cvt_pk_bf16_f32 v62, v113, v112
	v_cvt_pk_bf16_f32 v63, v111, v110
	v_add_f32_e32 v1, v1, v125
	v_add_f32_e32 v1, v1, v124
	v_add_f32_e32 v1, v1, v123
	v_add_f32_e32 v1, v1, v122
	s_nop 0
	v_mfma_f32_32x32x16_bf16 v[18:33], v[150:153], v[60:63], v[18:33]
	v_add_f32_e32 v1, v1, v109
	v_add_f32_e32 v1, v1, v108
	v_add_f32_e32 v1, v1, v107
	v_add_f32_e32 v1, v1, v106
	v_exp_f32_e32 v196, v87
	v_exp_f32_e32 v197, v88
	s_waitcnt lgkmcnt(0)
	v_mfma_f32_32x32x16_bf16 v[2:17], v[200:203], v[60:63], v[2:17]
	v_add_f32_e32 v1, v1, v113
	v_add_f32_e32 v1, v1, v112
	v_add_f32_e32 v1, v1, v111
	v_add_f32_e32 v1, v1, v110
	s_setprio 2
	s_waitcnt lgkmcnt(0)
	s_barrier
	ds_read_b128 v[240:243], v165 offset:18432
	ds_read_b128 v[244:247], v165 offset:23040
	ds_read_b128 v[130:133], v165 offset:18464
	ds_read_b128 v[146:149], v165 offset:23072
	s_waitcnt lgkmcnt(2)
	v_mfma_f32_32x32x16_bf16 v[114:129], v[240:243], v[158:161], v[34:49]
	v_exp_f32_e32 v198, v89
	s_waitcnt lgkmcnt(1)
	v_mfma_f32_32x32x16_bf16 v[98:113], v[244:247], v[158:161], v[34:49]
	v_exp_f32_e32 v199, v90
	v_exp_f32_e32 v200, v91
	v_exp_f32_e32 v201, v92
	v_exp_f32_e32 v202, v93
	v_exp_f32_e32 v134, v94
	v_exp_f32_e32 v135, v95
	v_exp_f32_e32 v136, v96
	v_exp_f32_e32 v137, v97
	v_mfma_f32_32x32x16_bf16 v[114:129], v[130:133], v[154:157], v[114:129]
	v_exp_f32_e32 v96, v66
	v_exp_f32_e32 v97, v67
	v_exp_f32_e32 v203, v68
	v_exp_f32_e32 v204, v69
	v_exp_f32_e32 v130, v70
	v_exp_f32_e32 v131, v71
	v_exp_f32_e32 v132, v72
	v_exp_f32_e32 v133, v73
	s_waitcnt lgkmcnt(0)
	v_mfma_f32_32x32x16_bf16 v[98:113], v[146:149], v[154:157], v[98:113]
	v_exp_f32_e32 v205, v74
	v_exp_f32_e32 v206, v75
	v_exp_f32_e32 v207, v76
	v_exp_f32_e32 v209, v78
	v_exp_f32_e32 v210, v79
	v_exp_f32_e32 v211, v80
	v_exp_f32_e32 v212, v81
	s_cmp_gt_i32 s25, 2
	s_cselect_b32 s27, -3, 2
	s_add_i32 s27, s27, s25
	v_add_u32_e32 v88, s26, v163
	s_add_i32 s26, s23, -6
	s_mulk_i32 s27, 0x2400
	s_min_u32 s26, s26, s13
	v_add_u32_e32 v51, s27, v182
	s_min_u32 s24, s24, s13
	s_lshl_b32 s92, s26, 13
	s_waitcnt vmcnt(3)
	ds_write_b128 v182, v[138:141]
	s_waitcnt vmcnt(2)
	ds_write_b128 v51, v[142:145] offset:36864
	v_add_f32_e32 v1, v50, v1
	s_add_u32 vcc_lo, s100, s92
	s_addc_u32 vcc_hi, s101, 0
	global_load_dwordx4 v[146:149], v248, vcc
	s_lshl_b32 s92, s24, 7
	s_add_u32 vcc_lo, s98, s92
	s_addc_u32 vcc_hi, s99, 0
	global_load_dwordx4 v[150:153], v249, vcc
	ds_read_b128 v[240:243], v165 offset:27648
	ds_read_b128 v[244:247], v165 offset:32256
	ds_read_b128 v[60:63], v88 offset:41472
	ds_read_b128 v[64:67], v88 offset:36864
	ds_read_b128 v[68:71], v88 offset:36896
	ds_read_b128 v[72:75], v88 offset:41504
	ds_read_b128 v[76:79], v88 offset:36928
	ds_read_b128 v[80:83], v88 offset:41536
	ds_read_b128 v[84:87], v88 offset:36960
	ds_read_b128 v[88:91], v88 offset:41568
	s_add_i32 s27, s25, 1
	s_setprio 1
	v_cvt_pk_bf16_f32 v92, v185, v186
	v_cvt_pk_bf16_f32 v93, v187, v194
	v_cvt_pk_bf16_f32 v94, v195, v196
	v_cvt_pk_bf16_f32 v95, v197, v198
	s_waitcnt lgkmcnt(6)
	s_nop 0
	v_mfma_f32_32x32x16_bf16 v[18:33], v[64:67], v[92:95], v[18:33]
	v_mov_b32_e32 v213, v185
	v_add_f32_e32 v213, v213, v186
	v_add_f32_e32 v213, v213, v187
	v_add_f32_e32 v213, v213, v194
	v_exp_f32_e32 v185, v114
	v_exp_f32_e32 v186, v115
	s_nop 0
	v_mfma_f32_32x32x16_bf16 v[2:17], v[60:63], v[92:95], v[2:17]
	v_cvt_pk_bf16_f32 v64, v199, v200
	v_cvt_pk_bf16_f32 v65, v201, v202
	v_cvt_pk_bf16_f32 v66, v134, v135
	v_cvt_pk_bf16_f32 v67, v136, v137
	v_add_f32_e32 v213, v213, v195
	v_add_f32_e32 v213, v213, v196
	v_add_f32_e32 v213, v213, v197
	v_add_f32_e32 v213, v213, v198
	s_waitcnt lgkmcnt(5)
	v_mfma_f32_32x32x16_bf16 v[18:33], v[68:71], v[64:67], v[18:33]
	v_add_f32_e32 v213, v213, v199
	v_add_f32_e32 v213, v213, v200
	v_add_f32_e32 v213, v213, v201
	v_add_f32_e32 v213, v213, v202
	v_exp_f32_e32 v187, v116
	v_exp_f32_e32 v194, v117
	s_waitcnt lgkmcnt(4)
	v_mfma_f32_32x32x16_bf16 v[2:17], v[72:75], v[64:67], v[2:17]
	v_cvt_pk_bf16_f32 v60, v96, v97
	v_cvt_pk_bf16_f32 v61, v203, v204
	v_cvt_pk_bf16_f32 v62, v130, v131
	v_cvt_pk_bf16_f32 v63, v132, v133
	v_add_f32_e32 v213, v213, v134
	v_add_f32_e32 v213, v213, v135
	v_add_f32_e32 v213, v213, v136
	v_add_f32_e32 v213, v213, v137
	s_waitcnt lgkmcnt(3)
	v_mfma_f32_32x32x16_bf16 v[18:33], v[76:79], v[60:63], v[18:33]
	v_add_f32_e32 v213, v213, v96
	v_add_f32_e32 v213, v213, v97
	v_add_f32_e32 v213, v213, v203
	v_add_f32_e32 v213, v213, v204
	v_exp_f32_e32 v195, v118
	v_exp_f32_e32 v196, v119
	s_waitcnt lgkmcnt(2)
	v_mfma_f32_32x32x16_bf16 v[2:17], v[80:83], v[60:63], v[2:17]
	v_cvt_pk_bf16_f32 v64, v205, v206
	v_cvt_pk_bf16_f32 v65, v207, v208
	v_cvt_pk_bf16_f32 v66, v209, v210
	v_cvt_pk_bf16_f32 v67, v211, v212
	v_add_f32_e32 v213, v213, v130
	v_add_f32_e32 v213, v213, v131
	v_add_f32_e32 v213, v213, v132
	v_add_f32_e32 v213, v213, v133
	s_waitcnt lgkmcnt(1)
	v_mfma_f32_32x32x16_bf16 v[18:33], v[84:87], v[64:67], v[18:33]
	v_add_f32_e32 v213, v213, v205
	v_add_f32_e32 v213, v213, v206
	v_add_f32_e32 v213, v213, v207
	v_add_f32_e32 v213, v213, v208
	v_exp_f32_e32 v197, v120
	v_exp_f32_e32 v198, v121
	s_waitcnt lgkmcnt(0)
	v_mfma_f32_32x32x16_bf16 v[2:17], v[88:91], v[64:67], v[2:17]
	v_add_f32_e32 v213, v213, v209
	v_add_f32_e32 v213, v213, v210
	v_add_f32_e32 v213, v213, v211
	v_add_f32_e32 v213, v213, v212
	s_setprio 0
	ds_read_b128 v[64:67], v165 offset:27680
	ds_read_b128 v[72:75], v165 offset:32288
	s_cmp_lg_u32 s25, 4
	s_cselect_b32 s24, s27, 0
	s_waitcnt lgkmcnt(2)
	v_mfma_f32_32x32x16_bf16 v[130:145], v[240:243], v[158:161], v[34:49]
	s_waitcnt lgkmcnt(1)
	v_mfma_f32_32x32x16_bf16 v[82:97], v[244:247], v[158:161], v[34:49]
	v_exp_f32_e32 v199, v122
	v_exp_f32_e32 v200, v123
	v_exp_f32_e32 v201, v124
	v_exp_f32_e32 v202, v125
	v_exp_f32_e32 v122, v126
	v_exp_f32_e32 v123, v127
	v_exp_f32_e32 v124, v128
	v_exp_f32_e32 v125, v129
	v_mfma_f32_32x32x16_bf16 v[130:145], v[64:67], v[154:157], v[130:145]
	v_exp_f32_e32 v126, v98
	v_exp_f32_e32 v127, v99
	v_exp_f32_e32 v128, v100
	v_exp_f32_e32 v129, v101
	v_exp_f32_e32 v203, v102
	v_exp_f32_e32 v204, v103
	v_exp_f32_e32 v205, v104
	v_exp_f32_e32 v206, v105
	s_waitcnt lgkmcnt(0)
	v_mfma_f32_32x32x16_bf16 v[82:97], v[72:75], v[154:157], v[82:97]
	v_exp_f32_e32 v102, v106
	v_exp_f32_e32 v103, v107
	v_exp_f32_e32 v104, v108
	v_exp_f32_e32 v105, v109
	v_exp_f32_e32 v106, v110
	v_exp_f32_e32 v107, v111
	v_exp_f32_e32 v108, v112
	v_exp_f32_e32 v109, v113
	s_cmp_gt_i32 s24, 2
	s_cselect_b32 s25, -3, 2
	s_add_i32 s25, s25, s24
	s_mulk_i32 s25, 0x2400
	v_add_u32_e32 v50, s25, v182
	s_add_i32 s25, s24, 1
	s_cmp_lg_u32 s24, 4
	s_cselect_b32 s24, s25, 0
	s_add_i32 s25, s23, -5
	s_min_u32 s25, s25, s13
	s_lshl_b32 s92, s25, 13
	s_waitcnt vmcnt(3)
	ds_write_b128 v182, v[52:55] offset:9216
	s_waitcnt vmcnt(2)
	ds_write_b128 v50, v[56:59] offset:36864
	s_add_u32 vcc_lo, s100, s92
	s_addc_u32 vcc_hi, s101, 0
	global_load_dwordx4 v[118:121], v248, vcc
	s_lshl_b32 s92, s26, 7
	s_add_u32 vcc_lo, s98, s92
	s_addc_u32 vcc_hi, s99, 0
	global_load_dwordx4 v[114:117], v249, vcc
	s_mul_i32 s26, s24, 0x2400
	s_add_i32 s27, s26, 0xffffdc00
	s_cmp_lg_u32 s24, 0
	s_cselect_b32 s27, s27, 0x9000
	v_add_u32_e32 v78, s27, v163
	ds_read_b128 v[50:53], v78 offset:36864
	ds_read_b128 v[54:57], v78 offset:36896
	ds_read_b128 v[58:61], v78 offset:41472
	ds_read_b128 v[62:65], v78 offset:41504
	ds_read_b128 v[66:69], v78 offset:36928
	ds_read_b128 v[70:73], v78 offset:36960
	ds_read_b128 v[74:77], v78 offset:41536
	ds_read_b128 v[78:81], v78 offset:41568
	s_setprio 3
	v_cvt_pk_bf16_f32 v98, v185, v186
	v_cvt_pk_bf16_f32 v99, v187, v194
	v_cvt_pk_bf16_f32 v100, v195, v196
	v_cvt_pk_bf16_f32 v101, v197, v198
	s_waitcnt lgkmcnt(7)
	s_nop 0
	v_mfma_f32_32x32x16_bf16 v[18:33], v[50:53], v[98:101], v[18:33]
	v_mov_b32_e32 v110, v185
	v_add_f32_e32 v110, v110, v186
	v_add_f32_e32 v110, v110, v187
	v_add_f32_e32 v110, v110, v194
	v_exp_f32_e32 v185, v130
	v_exp_f32_e32 v186, v131
	s_waitcnt lgkmcnt(5)
	v_mfma_f32_32x32x16_bf16 v[2:17], v[58:61], v[98:101], v[2:17]
	v_cvt_pk_bf16_f32 v50, v199, v200
	v_cvt_pk_bf16_f32 v51, v201, v202
	v_cvt_pk_bf16_f32 v52, v122, v123
	v_cvt_pk_bf16_f32 v53, v124, v125
	v_add_f32_e32 v110, v110, v195
	v_add_f32_e32 v110, v110, v196
	v_add_f32_e32 v110, v110, v197
	v_add_f32_e32 v110, v110, v198
	s_nop 0
	v_mfma_f32_32x32x16_bf16 v[18:33], v[54:57], v[50:53], v[18:33]
	v_add_f32_e32 v110, v110, v199
	v_add_f32_e32 v110, v110, v200
	v_add_f32_e32 v110, v110, v201
	v_add_f32_e32 v110, v110, v202
	v_exp_f32_e32 v187, v132
	v_exp_f32_e32 v194, v133
	s_waitcnt lgkmcnt(4)
	v_mfma_f32_32x32x16_bf16 v[2:17], v[62:65], v[50:53], v[2:17]
	v_cvt_pk_bf16_f32 v54, v126, v127
	v_cvt_pk_bf16_f32 v55, v128, v129
	v_cvt_pk_bf16_f32 v56, v203, v204
	v_cvt_pk_bf16_f32 v57, v205, v206
	v_add_f32_e32 v110, v110, v122
	v_add_f32_e32 v110, v110, v123
	v_add_f32_e32 v110, v110, v124
	v_add_f32_e32 v110, v110, v125
	s_waitcnt lgkmcnt(3)
	v_mfma_f32_32x32x16_bf16 v[18:33], v[66:69], v[54:57], v[18:33]
	v_add_f32_e32 v110, v110, v126
	v_add_f32_e32 v110, v110, v127
	v_add_f32_e32 v110, v110, v128
	v_add_f32_e32 v110, v110, v129
	v_exp_f32_e32 v195, v134
	v_exp_f32_e32 v196, v135
	s_waitcnt lgkmcnt(1)
	v_mfma_f32_32x32x16_bf16 v[2:17], v[74:77], v[54:57], v[2:17]
	v_cvt_pk_bf16_f32 v50, v102, v103
	v_cvt_pk_bf16_f32 v51, v104, v105
	v_cvt_pk_bf16_f32 v52, v106, v107
	v_cvt_pk_bf16_f32 v53, v108, v109
	v_add_f32_e32 v110, v110, v203
	v_add_f32_e32 v110, v110, v204
	v_add_f32_e32 v110, v110, v205
	v_add_f32_e32 v110, v110, v206
	s_nop 0
	v_mfma_f32_32x32x16_bf16 v[18:33], v[70:73], v[50:53], v[18:33]
	v_add_f32_e32 v110, v110, v102
	v_add_f32_e32 v110, v110, v103
	v_add_f32_e32 v110, v110, v104
	v_add_f32_e32 v110, v110, v105
	v_exp_f32_e32 v197, v136
	v_exp_f32_e32 v198, v137
	s_waitcnt lgkmcnt(0)
	v_mfma_f32_32x32x16_bf16 v[2:17], v[78:81], v[50:53], v[2:17]
	v_add_f32_e32 v110, v110, v106
	v_add_f32_e32 v110, v110, v107
	v_add_f32_e32 v110, v110, v108
	v_add_f32_e32 v110, v110, v109
	s_setprio 2
	s_waitcnt lgkmcnt(0)
	s_barrier
	ds_read_b128 v[240:243], v165
	ds_read_b128 v[244:247], v165 offset:4608
	ds_read_b128 v[102:105], v165 offset:32
	ds_read_b128 v[106:109], v165 offset:4640
	v_add_f32_e32 v1, v1, v213
	s_waitcnt lgkmcnt(2)
	v_mfma_f32_32x32x16_bf16 v[66:81], v[240:243], v[158:161], v[34:49]
	v_mfma_f32_32x32x16_bf16 v[50:65], v[244:247], v[158:161], v[34:49]
	v_exp_f32_e32 v134, v138
	v_exp_f32_e32 v135, v139
	v_exp_f32_e32 v136, v140
	v_exp_f32_e32 v137, v141
	v_exp_f32_e32 v138, v142
	v_exp_f32_e32 v139, v143
	v_exp_f32_e32 v140, v144
	v_exp_f32_e32 v141, v145
	s_waitcnt lgkmcnt(1)
	v_mfma_f32_32x32x16_bf16 v[66:81], v[102:105], v[154:157], v[66:81]
	v_exp_f32_e32 v142, v82
	v_exp_f32_e32 v143, v83
	v_exp_f32_e32 v144, v84
	v_exp_f32_e32 v145, v85
	v_exp_f32_e32 v199, v86
	v_exp_f32_e32 v200, v87
	v_exp_f32_e32 v201, v88
	v_exp_f32_e32 v202, v89
	s_waitcnt lgkmcnt(0)
	v_mfma_f32_32x32x16_bf16 v[50:65], v[106:109], v[154:157], v[50:65]
	v_exp_f32_e32 v203, v90
	v_exp_f32_e32 v204, v91
	v_exp_f32_e32 v205, v92
	v_exp_f32_e32 v206, v93
	v_exp_f32_e32 v207, v94
	v_exp_f32_e32 v208, v95
	v_exp_f32_e32 v209, v96
	v_exp_f32_e32 v210, v97
	s_cmp_gt_i32 s24, 2
	s_cselect_b32 s27, -3, 2
	s_add_i32 s27, s27, s24
	s_mulk_i32 s27, 0x2400
	v_add_u32_e32 v82, s27, v182
	s_mov_b32 s27, 0x18950000
	s_waitcnt vmcnt(3)
	ds_write_b128 v182, v[146:149] offset:18432
	s_waitcnt vmcnt(2)
	ds_write_b128 v82, v[150:153] offset:36864
	v_add_co_u32_e32 v82, vcc, s27, v178
	s_lshl_b32 s92, s25, 7
	s_nop 0
	v_addc_co_u32_e32 v83, vcc, 0, v179, vcc
	global_load_dwordx4 v[126:129], v[82:83], off
	s_add_u32 vcc_lo, s98, s92
	s_addc_u32 vcc_hi, s99, 0
	global_load_dwordx4 v[122:125], v249, vcc
	v_add_u32_e32 v111, s26, v163
	v_add_f32_e32 v1, v1, v110
	ds_read_b128 v[240:243], v165 offset:9216
	ds_read_b128 v[244:247], v165 offset:13824
	ds_read_b128 v[82:85], v111 offset:41472
	ds_read_b128 v[86:89], v111 offset:36864
	ds_read_b128 v[90:93], v111 offset:36896
	ds_read_b128 v[94:97], v111 offset:41504
	ds_read_b128 v[98:101], v111 offset:36928
	ds_read_b128 v[102:105], v111 offset:41536
	ds_read_b128 v[106:109], v111 offset:36960
	ds_read_b128 v[110:113], v111 offset:41568
	s_add_i32 s26, s24, 1
	s_setprio 1
	v_cvt_pk_bf16_f32 v130, v185, v186
	v_cvt_pk_bf16_f32 v131, v187, v194
	v_cvt_pk_bf16_f32 v132, v195, v196
	v_cvt_pk_bf16_f32 v133, v197, v198
	s_waitcnt lgkmcnt(6)
	s_nop 0
	v_mfma_f32_32x32x16_bf16 v[18:33], v[86:89], v[130:133], v[18:33]
	v_mov_b32_e32 v146, v185
	v_add_f32_e32 v146, v146, v186
	v_add_f32_e32 v146, v146, v187
	v_add_f32_e32 v146, v146, v194
	v_exp_f32_e32 v147, v70
	v_exp_f32_e32 v148, v71
	s_nop 0
	v_mfma_f32_32x32x16_bf16 v[2:17], v[82:85], v[130:133], v[2:17]
	v_cvt_pk_bf16_f32 v86, v134, v135
	v_cvt_pk_bf16_f32 v87, v136, v137
	v_cvt_pk_bf16_f32 v88, v138, v139
	v_cvt_pk_bf16_f32 v89, v140, v141
	v_add_f32_e32 v146, v146, v195
	v_add_f32_e32 v146, v146, v196
	v_add_f32_e32 v146, v146, v197
	v_add_f32_e32 v146, v146, v198
	s_waitcnt lgkmcnt(5)
	v_mfma_f32_32x32x16_bf16 v[18:33], v[90:93], v[86:89], v[18:33]
	v_add_f32_e32 v146, v146, v134
	v_add_f32_e32 v146, v146, v135
	v_add_f32_e32 v146, v146, v136
	v_add_f32_e32 v146, v146, v137
	v_exp_f32_e32 v149, v72
	v_exp_f32_e32 v150, v73
	s_waitcnt lgkmcnt(4)
	v_mfma_f32_32x32x16_bf16 v[2:17], v[94:97], v[86:89], v[2:17]
	v_cvt_pk_bf16_f32 v82, v142, v143
	v_cvt_pk_bf16_f32 v83, v144, v145
	v_cvt_pk_bf16_f32 v84, v199, v200
	v_cvt_pk_bf16_f32 v85, v201, v202
	v_add_f32_e32 v146, v146, v138
	v_add_f32_e32 v146, v146, v139
	v_add_f32_e32 v146, v146, v140
	v_add_f32_e32 v146, v146, v141
	s_waitcnt lgkmcnt(3)
	v_mfma_f32_32x32x16_bf16 v[18:33], v[98:101], v[82:85], v[18:33]
	v_add_f32_e32 v146, v146, v142
	v_add_f32_e32 v146, v146, v143
	v_add_f32_e32 v146, v146, v144
	v_add_f32_e32 v146, v146, v145
	v_exp_f32_e32 v142, v66
	v_exp_f32_e32 v143, v67
	s_waitcnt lgkmcnt(2)
	v_mfma_f32_32x32x16_bf16 v[2:17], v[102:105], v[82:85], v[2:17]
	v_cvt_pk_bf16_f32 v86, v203, v204
	v_cvt_pk_bf16_f32 v87, v205, v206
	v_cvt_pk_bf16_f32 v88, v207, v208
	v_cvt_pk_bf16_f32 v89, v209, v210
	v_add_f32_e32 v146, v146, v199
	v_add_f32_e32 v146, v146, v200
	v_add_f32_e32 v146, v146, v201
	v_add_f32_e32 v146, v146, v202
	s_waitcnt lgkmcnt(1)
	v_mfma_f32_32x32x16_bf16 v[18:33], v[106:109], v[86:89], v[18:33]
	v_add_f32_e32 v146, v146, v203
	v_add_f32_e32 v146, v146, v204
	v_add_f32_e32 v146, v146, v205
	v_add_f32_e32 v146, v146, v206
	v_exp_f32_e32 v144, v68
	v_exp_f32_e32 v145, v69
	s_waitcnt lgkmcnt(0)
	v_mfma_f32_32x32x16_bf16 v[2:17], v[110:113], v[86:89], v[2:17]
	v_add_f32_e32 v146, v146, v207
	v_add_f32_e32 v146, v146, v208
	v_add_f32_e32 v146, v146, v209
	v_add_f32_e32 v146, v146, v210
	s_setprio 0
	ds_read_b128 v[130:133], v165 offset:9248
	ds_read_b128 v[138:141], v165 offset:13856
	s_cmp_lg_u32 s24, 4
	s_cselect_b32 s24, s26, 0
	s_waitcnt lgkmcnt(2)
	v_mfma_f32_32x32x16_bf16 v[98:113], v[240:243], v[158:161], v[34:49]
	s_waitcnt lgkmcnt(1)
	v_mfma_f32_32x32x16_bf16 v[82:97], v[244:247], v[158:161], v[34:49]
	v_exp_f32_e32 v151, v74
	v_exp_f32_e32 v152, v75
	v_exp_f32_e32 v153, v76
	v_exp_f32_e32 v178, v77
	v_exp_f32_e32 v134, v78
	v_exp_f32_e32 v135, v79
	v_exp_f32_e32 v136, v80
	v_exp_f32_e32 v137, v81
	v_mfma_f32_32x32x16_bf16 v[98:113], v[130:133], v[154:157], v[98:113]
	v_exp_f32_e32 v179, v50
	v_exp_f32_e32 v185, v51
	v_exp_f32_e32 v186, v52
	v_exp_f32_e32 v187, v53
	v_exp_f32_e32 v194, v54
	v_exp_f32_e32 v195, v55
	v_exp_f32_e32 v196, v56
	v_exp_f32_e32 v197, v57
	s_waitcnt lgkmcnt(0)
	v_mfma_f32_32x32x16_bf16 v[82:97], v[138:141], v[154:157], v[82:97]
	v_exp_f32_e32 v198, v58
	v_exp_f32_e32 v199, v59
	v_exp_f32_e32 v200, v60
	v_exp_f32_e32 v201, v61
	v_exp_f32_e32 v138, v62
	v_exp_f32_e32 v139, v63
	v_exp_f32_e32 v140, v64
	v_exp_f32_e32 v141, v65
	s_cmp_gt_i32 s24, 2
	s_cselect_b32 s25, -3, 2
	s_add_i32 s25, s25, s24
	s_mulk_i32 s25, 0x2400
	v_add_u32_e32 v50, s25, v182
	s_add_i32 s25, s24, 1
	s_cmp_lg_u32 s24, 4
	s_cselect_b32 s25, s25, 0
	s_add_i32 s24, s23, -3
	s_min_u32 s26, s24, s13
	s_lshl_b32 s92, s26, 13
	s_waitcnt vmcnt(3)
	ds_write_b128 v182, v[118:121] offset:27648
	s_waitcnt vmcnt(2)
	ds_write_b128 v50, v[114:117] offset:36864
	s_add_u32 vcc_lo, s100, s92
	s_addc_u32 vcc_hi, s101, 0
	global_load_dwordx4 v[118:121], v248, vcc
	global_load_dwordx4 v[114:117], v[176:177], off offset:1024
	s_mul_i32 s27, s25, 0x2400
	s_add_i32 s28, s27, 0xffffdc00
	s_cmp_lg_u32 s25, 0
	s_cselect_b32 s28, s28, 0x9000
	v_add_u32_e32 v78, s28, v163
	ds_read_b128 v[50:53], v78 offset:36864
	ds_read_b128 v[54:57], v78 offset:36896
	ds_read_b128 v[58:61], v78 offset:41472
	ds_read_b128 v[62:65], v78 offset:41504
	ds_read_b128 v[66:69], v78 offset:36928
	ds_read_b128 v[70:73], v78 offset:36960
	ds_read_b128 v[74:77], v78 offset:41536
	ds_read_b128 v[78:81], v78 offset:41568
	s_setprio 3
	v_cvt_pk_bf16_f32 v130, v142, v143
	v_cvt_pk_bf16_f32 v131, v144, v145
	v_cvt_pk_bf16_f32 v132, v147, v148
	v_cvt_pk_bf16_f32 v133, v149, v150
	s_waitcnt lgkmcnt(7)
	s_nop 0
	v_mfma_f32_32x32x16_bf16 v[18:33], v[50:53], v[130:133], v[18:33]
	v_mov_b32_e32 v176, v142
	v_add_f32_e32 v176, v176, v143
	v_add_f32_e32 v176, v176, v144
	v_add_f32_e32 v176, v176, v145
	v_exp_f32_e32 v142, v98
	v_exp_f32_e32 v143, v99
	s_waitcnt lgkmcnt(5)
	v_mfma_f32_32x32x16_bf16 v[2:17], v[58:61], v[130:133], v[2:17]
	v_cvt_pk_bf16_f32 v50, v151, v152
	v_cvt_pk_bf16_f32 v51, v153, v178
	v_cvt_pk_bf16_f32 v52, v134, v135
	v_cvt_pk_bf16_f32 v53, v136, v137
	v_add_f32_e32 v176, v176, v147
	v_add_f32_e32 v176, v176, v148
	v_add_f32_e32 v176, v176, v149
	v_add_f32_e32 v176, v176, v150
	s_nop 0
	v_mfma_f32_32x32x16_bf16 v[18:33], v[54:57], v[50:53], v[18:33]
	v_add_f32_e32 v176, v176, v151
	v_add_f32_e32 v176, v176, v152
	v_add_f32_e32 v176, v176, v153
	v_add_f32_e32 v176, v176, v178
	v_exp_f32_e32 v144, v100
	v_exp_f32_e32 v145, v101
	s_waitcnt lgkmcnt(4)
	v_mfma_f32_32x32x16_bf16 v[2:17], v[62:65], v[50:53], v[2:17]
	v_cvt_pk_bf16_f32 v54, v179, v185
	v_cvt_pk_bf16_f32 v55, v186, v187
	v_cvt_pk_bf16_f32 v56, v194, v195
	v_cvt_pk_bf16_f32 v57, v196, v197
	v_add_f32_e32 v176, v176, v134
	v_add_f32_e32 v176, v176, v135
	v_add_f32_e32 v176, v176, v136
	v_add_f32_e32 v176, v176, v137
	s_waitcnt lgkmcnt(3)
	v_mfma_f32_32x32x16_bf16 v[18:33], v[66:69], v[54:57], v[18:33]
	v_add_f32_e32 v176, v176, v179
	v_add_f32_e32 v176, v176, v185
	v_add_f32_e32 v176, v176, v186
	v_add_f32_e32 v176, v176, v187
	v_exp_f32_e32 v147, v103
	v_exp_f32_e32 v148, v104
	s_waitcnt lgkmcnt(1)
	v_mfma_f32_32x32x16_bf16 v[2:17], v[74:77], v[54:57], v[2:17]
	v_cvt_pk_bf16_f32 v50, v198, v199
	v_cvt_pk_bf16_f32 v51, v200, v201
	v_cvt_pk_bf16_f32 v52, v138, v139
	v_cvt_pk_bf16_f32 v53, v140, v141
	v_add_f32_e32 v176, v176, v194
	v_add_f32_e32 v176, v176, v195
	v_add_f32_e32 v176, v176, v196
	v_add_f32_e32 v176, v176, v197
	s_nop 0
	v_mfma_f32_32x32x16_bf16 v[18:33], v[70:73], v[50:53], v[18:33]
	v_add_f32_e32 v176, v176, v198
	v_add_f32_e32 v176, v176, v199
	v_add_f32_e32 v176, v176, v200
	v_add_f32_e32 v176, v176, v201
	v_exp_f32_e32 v149, v105
	v_exp_f32_e32 v150, v106
	s_waitcnt lgkmcnt(0)
	v_mfma_f32_32x32x16_bf16 v[2:17], v[78:81], v[50:53], v[2:17]
	v_add_f32_e32 v176, v176, v138
	v_add_f32_e32 v176, v176, v139
	v_add_f32_e32 v176, v176, v140
	v_add_f32_e32 v176, v176, v141
	s_setprio 2
	s_waitcnt lgkmcnt(0)
	s_barrier
	ds_read_b128 v[240:243], v165 offset:18432
	ds_read_b128 v[244:247], v165 offset:23040
	ds_read_b128 v[134:137], v165 offset:18464
	ds_read_b128 v[138:141], v165 offset:23072
	v_add_f32_e32 v1, v1, v146
	s_waitcnt lgkmcnt(2)
	v_mfma_f32_32x32x16_bf16 v[66:81], v[240:243], v[158:161], v[34:49]
	v_exp_f32_e32 v146, v102
	v_mfma_f32_32x32x16_bf16 v[50:65], v[244:247], v[158:161], v[34:49]
	v_exp_f32_e32 v151, v107
	v_exp_f32_e32 v152, v108
	v_exp_f32_e32 v153, v109
	v_exp_f32_e32 v177, v110
	v_exp_f32_e32 v178, v111
	v_exp_f32_e32 v179, v112
	v_exp_f32_e32 v185, v113
	s_waitcnt lgkmcnt(1)
	v_mfma_f32_32x32x16_bf16 v[66:81], v[134:137], v[154:157], v[66:81]
	v_exp_f32_e32 v186, v82
	v_exp_f32_e32 v187, v83
	v_exp_f32_e32 v194, v84
	v_exp_f32_e32 v195, v85
	v_exp_f32_e32 v134, v86
	v_exp_f32_e32 v135, v87
	v_exp_f32_e32 v136, v88
	v_exp_f32_e32 v137, v89
	s_waitcnt lgkmcnt(0)
	v_mfma_f32_32x32x16_bf16 v[50:65], v[138:141], v[154:157], v[50:65]
	v_exp_f32_e32 v196, v90
	v_exp_f32_e32 v197, v91
	v_exp_f32_e32 v198, v92
	v_exp_f32_e32 v199, v93
	v_exp_f32_e32 v138, v94
	v_exp_f32_e32 v139, v95
	v_exp_f32_e32 v140, v96
	v_exp_f32_e32 v141, v97
	s_cmp_gt_i32 s25, 2
	s_cselect_b32 s28, -3, 2
	s_waitcnt vmcnt(3)
	ds_write_b128 v182, v[126:129]
	s_add_i32 s28, s28, s25
	v_add_u32_e32 v126, s27, v163
	s_add_i32 s27, s23, -2
	s_mulk_i32 s28, 0x2400
	s_min_u32 s27, s27, s13
	v_add_u32_e32 v82, s28, v182
	s_lshl_b32 s92, s27, 13
	s_waitcnt vmcnt(2)
	ds_write_b128 v82, v[122:125] offset:36864
	s_add_u32 vcc_lo, s100, s92
	s_addc_u32 vcc_hi, s101, 0
	global_load_dwordx4 v[98:101], v248, vcc
	s_lshl_b32 s92, s26, 7
	s_add_u32 vcc_lo, s98, s92
	s_addc_u32 vcc_hi, s99, 0
	global_load_dwordx4 v[102:105], v249, vcc
	ds_read_b128 v[240:243], v165 offset:27648
	ds_read_b128 v[244:247], v165 offset:32256
	ds_read_b128 v[82:85], v126 offset:41472
	ds_read_b128 v[86:89], v126 offset:36864
	ds_read_b128 v[90:93], v126 offset:36896
	ds_read_b128 v[94:97], v126 offset:41504
	ds_read_b128 v[106:109], v126 offset:36928
	ds_read_b128 v[110:113], v126 offset:41536
	ds_read_b128 v[122:125], v126 offset:36960
	ds_read_b128 v[126:129], v126 offset:41568
	v_add_f32_e32 v1, v1, v176
	s_add_i32 s28, s25, 1
	s_setprio 1
	v_cvt_pk_bf16_f32 v130, v142, v143
	v_cvt_pk_bf16_f32 v131, v144, v145
	v_cvt_pk_bf16_f32 v132, v146, v147
	v_cvt_pk_bf16_f32 v133, v148, v149
	s_waitcnt lgkmcnt(6)
	s_nop 0
	v_mfma_f32_32x32x16_bf16 v[18:33], v[86:89], v[130:133], v[18:33]
	v_mov_b32_e32 v176, v142
	v_add_f32_e32 v176, v176, v143
	v_add_f32_e32 v176, v176, v144
	v_add_f32_e32 v176, v176, v145
	v_exp_f32_e32 v200, v60
	v_exp_f32_e32 v201, v61
	s_nop 0
	v_mfma_f32_32x32x16_bf16 v[2:17], v[82:85], v[130:133], v[2:17]
	v_cvt_pk_bf16_f32 v86, v150, v151
	v_cvt_pk_bf16_f32 v87, v152, v153
	v_cvt_pk_bf16_f32 v88, v177, v178
	v_cvt_pk_bf16_f32 v89, v179, v185
	v_add_f32_e32 v176, v176, v146
	v_add_f32_e32 v176, v176, v147
	v_add_f32_e32 v176, v176, v148
	v_add_f32_e32 v176, v176, v149
	s_waitcnt lgkmcnt(5)
	v_mfma_f32_32x32x16_bf16 v[18:33], v[90:93], v[86:89], v[18:33]
	v_add_f32_e32 v176, v176, v150
	v_add_f32_e32 v176, v176, v151
	v_add_f32_e32 v176, v176, v152
	v_add_f32_e32 v176, v176, v153
	v_exp_f32_e32 v130, v70
	v_exp_f32_e32 v131, v71
	s_waitcnt lgkmcnt(4)
	v_mfma_f32_32x32x16_bf16 v[2:17], v[94:97], v[86:89], v[2:17]
	v_cvt_pk_bf16_f32 v82, v186, v187
	v_cvt_pk_bf16_f32 v83, v194, v195
	v_cvt_pk_bf16_f32 v84, v134, v135
	v_cvt_pk_bf16_f32 v85, v136, v137
	v_add_f32_e32 v176, v176, v177
	v_add_f32_e32 v176, v176, v178
	v_add_f32_e32 v176, v176, v179
	v_add_f32_e32 v176, v176, v185
	s_waitcnt lgkmcnt(3)
	v_mfma_f32_32x32x16_bf16 v[18:33], v[106:109], v[82:85], v[18:33]
	v_add_f32_e32 v176, v176, v186
	v_add_f32_e32 v176, v176, v187
	v_add_f32_e32 v176, v176, v194
	v_add_f32_e32 v176, v176, v195
	v_exp_f32_e32 v132, v72
	v_exp_f32_e32 v133, v73
	s_waitcnt lgkmcnt(2)
	v_mfma_f32_32x32x16_bf16 v[2:17], v[110:113], v[82:85], v[2:17]
	v_cvt_pk_bf16_f32 v86, v196, v197
	v_cvt_pk_bf16_f32 v87, v198, v199
	v_cvt_pk_bf16_f32 v88, v138, v139
	v_cvt_pk_bf16_f32 v89, v140, v141
	v_add_f32_e32 v176, v176, v134
	v_add_f32_e32 v176, v176, v135
	v_add_f32_e32 v176, v176, v136
	v_add_f32_e32 v176, v176, v137
	s_waitcnt lgkmcnt(1)
	v_mfma_f32_32x32x16_bf16 v[18:33], v[122:125], v[86:89], v[18:33]
	v_add_f32_e32 v176, v176, v196
	v_add_f32_e32 v176, v176, v197
	v_add_f32_e32 v176, v176, v198
	v_add_f32_e32 v176, v176, v199
	v_exp_f32_e32 v134, v74
	v_exp_f32_e32 v135, v75
	s_waitcnt lgkmcnt(0)
	v_mfma_f32_32x32x16_bf16 v[2:17], v[126:129], v[86:89], v[2:17]
	v_add_f32_e32 v176, v176, v138
	v_add_f32_e32 v176, v176, v139
	v_add_f32_e32 v176, v176, v140
	v_add_f32_e32 v176, v176, v141
	s_setprio 0
	ds_read_b128 v[106:109], v165 offset:27680
	ds_read_b128 v[122:125], v165 offset:32288
	s_cmp_lg_u32 s25, 4
	s_cselect_b32 s25, s28, 0
	s_waitcnt lgkmcnt(2)
	v_mfma_f32_32x32x16_bf16 v[138:153], v[240:243], v[158:161], v[34:49]
	v_exp_f32_e32 v126, v66
	v_exp_f32_e32 v127, v67
	v_exp_f32_e32 v128, v68
	v_exp_f32_e32 v129, v69
	s_waitcnt lgkmcnt(1)
	v_mfma_f32_32x32x16_bf16 v[82:97], v[244:247], v[158:161], v[34:49]
	v_exp_f32_e32 v136, v76
	v_exp_f32_e32 v137, v77
	v_exp_f32_e32 v177, v78
	v_exp_f32_e32 v178, v79
	v_exp_f32_e32 v179, v80
	v_exp_f32_e32 v185, v81
	v_mfma_f32_32x32x16_bf16 v[138:153], v[106:109], v[154:157], v[138:153]
	v_exp_f32_e32 v80, v50
	v_exp_f32_e32 v81, v51
	v_exp_f32_e32 v186, v52
	v_exp_f32_e32 v187, v53
	v_exp_f32_e32 v194, v54
	v_exp_f32_e32 v195, v55
	v_exp_f32_e32 v196, v56
	v_exp_f32_e32 v197, v57
	s_waitcnt lgkmcnt(0)
	v_mfma_f32_32x32x16_bf16 v[82:97], v[122:125], v[154:157], v[82:97]
	v_exp_f32_e32 v198, v58
	v_exp_f32_e32 v199, v59
	v_exp_f32_e32 v122, v62
	v_exp_f32_e32 v123, v63
	v_exp_f32_e32 v124, v64
	v_exp_f32_e32 v125, v65
	s_cmp_gt_i32 s25, 2
	s_cselect_b32 s26, -3, 2
	s_add_i32 s26, s26, s25
	s_mulk_i32 s26, 0x2400
	v_add_u32_e32 v50, s26, v182
	s_add_i32 s26, s25, 1
	s_cmp_lg_u32 s25, 4
	s_cselect_b32 s25, s26, 0
	s_add_i32 s26, s23, -1
	s_min_u32 s26, s26, s13
	s_lshl_b32 s92, s26, 13
	s_waitcnt vmcnt(3)
	ds_write_b128 v182, v[118:121] offset:9216
	s_waitcnt vmcnt(2)
	ds_write_b128 v50, v[114:117] offset:36864
	s_add_u32 vcc_lo, s100, s92
	s_addc_u32 vcc_hi, s101, 0
	global_load_dwordx4 v[56:59], v248, vcc
	s_lshl_b32 s92, s27, 7
	s_add_u32 vcc_lo, s98, s92
	s_addc_u32 vcc_hi, s99, 0
	global_load_dwordx4 v[52:55], v249, vcc
	s_nop 0
	s_mul_i32 s27, s25, 0x2400
	s_add_i32 s28, s27, 0xffffdc00
	s_cmp_lg_u32 s25, 0
	s_cselect_b32 s28, s28, 0x9000
	v_add_u32_e32 v50, s28, v163
	ds_read_b128 v[60:63], v50 offset:36864
	ds_read_b128 v[64:67], v50 offset:36896
	ds_read_b128 v[68:71], v50 offset:41472
	ds_read_b128 v[72:75], v50 offset:41504
	ds_read_b128 v[76:79], v50 offset:36928
	ds_read_b128 v[106:109], v50 offset:36960
	ds_read_b128 v[110:113], v50 offset:41536
	ds_read_b128 v[114:117], v50 offset:41568
	s_setprio 3
	v_cvt_pk_bf16_f32 v118, v126, v127
	v_cvt_pk_bf16_f32 v119, v128, v129
	v_cvt_pk_bf16_f32 v120, v130, v131
	v_cvt_pk_bf16_f32 v121, v132, v133
	s_waitcnt lgkmcnt(7)
	s_nop 0
	v_mfma_f32_32x32x16_bf16 v[18:33], v[60:63], v[118:121], v[18:33]
	v_mov_b32_e32 v50, v126
	v_add_f32_e32 v50, v50, v127
	v_add_f32_e32 v50, v50, v128
	v_add_f32_e32 v50, v50, v129
	v_exp_f32_e32 v202, v89
	v_exp_f32_e32 v203, v90
	s_waitcnt lgkmcnt(5)
	v_mfma_f32_32x32x16_bf16 v[2:17], v[68:71], v[118:121], v[2:17]
	v_cvt_pk_bf16_f32 v60, v134, v135
	v_cvt_pk_bf16_f32 v61, v136, v137
	v_cvt_pk_bf16_f32 v62, v177, v178
	v_cvt_pk_bf16_f32 v63, v179, v185
	v_add_f32_e32 v50, v50, v130
	v_add_f32_e32 v50, v50, v131
	v_add_f32_e32 v50, v50, v132
	v_add_f32_e32 v50, v50, v133
	s_nop 0
	v_mfma_f32_32x32x16_bf16 v[18:33], v[64:67], v[60:63], v[18:33]
	v_add_f32_e32 v50, v50, v134
	v_add_f32_e32 v50, v50, v135
	v_add_f32_e32 v50, v50, v136
	v_add_f32_e32 v50, v50, v137
	v_exp_f32_e32 v204, v91
	v_exp_f32_e32 v205, v92
	s_waitcnt lgkmcnt(4)
	v_mfma_f32_32x32x16_bf16 v[2:17], v[72:75], v[60:63], v[2:17]
	v_cvt_pk_bf16_f32 v64, v80, v81
	v_cvt_pk_bf16_f32 v65, v186, v187
	v_cvt_pk_bf16_f32 v66, v194, v195
	v_cvt_pk_bf16_f32 v67, v196, v197
	v_add_f32_e32 v50, v50, v177
	v_add_f32_e32 v50, v50, v178
	v_add_f32_e32 v50, v50, v179
	v_add_f32_e32 v50, v50, v185
	s_waitcnt lgkmcnt(3)
	v_mfma_f32_32x32x16_bf16 v[18:33], v[76:79], v[64:67], v[18:33]
	v_add_f32_e32 v50, v50, v80
	v_add_f32_e32 v50, v50, v81
	v_add_f32_e32 v50, v50, v186
	v_add_f32_e32 v50, v50, v187
	v_exp_f32_e32 v177, v139
	v_exp_f32_e32 v178, v140
	s_waitcnt lgkmcnt(1)
	v_mfma_f32_32x32x16_bf16 v[2:17], v[110:113], v[64:67], v[2:17]
	v_cvt_pk_bf16_f32 v60, v198, v199
	v_cvt_pk_bf16_f32 v61, v200, v201
	v_cvt_pk_bf16_f32 v62, v122, v123
	v_cvt_pk_bf16_f32 v63, v124, v125
	v_add_f32_e32 v50, v50, v194
	v_add_f32_e32 v50, v50, v195
	v_add_f32_e32 v50, v50, v196
	v_add_f32_e32 v50, v50, v197
	s_nop 0
	v_mfma_f32_32x32x16_bf16 v[18:33], v[106:109], v[60:63], v[18:33]
	v_add_f32_e32 v50, v50, v198
	v_add_f32_e32 v50, v50, v199
	v_add_f32_e32 v50, v50, v200
	v_add_f32_e32 v50, v50, v201
	v_exp_f32_e32 v179, v141
	v_exp_f32_e32 v185, v142
	s_waitcnt lgkmcnt(0)
	v_mfma_f32_32x32x16_bf16 v[2:17], v[114:117], v[60:63], v[2:17]
	v_add_f32_e32 v50, v50, v122
	v_add_f32_e32 v50, v50, v123
	v_add_f32_e32 v50, v50, v124
	v_add_f32_e32 v50, v50, v125
	s_setprio 2
	s_waitcnt lgkmcnt(0)
	s_barrier
	ds_read_b128 v[240:243], v165
	ds_read_b128 v[244:247], v165 offset:4608
	ds_read_b128 v[68:71], v165 offset:32
	ds_read_b128 v[72:75], v165 offset:4640
	v_add_f32_e32 v1, v1, v176
	s_waitcnt lgkmcnt(2)
	v_mfma_f32_32x32x16_bf16 v[122:137], v[240:243], v[158:161], v[34:49]
	v_exp_f32_e32 v176, v138
	v_exp_f32_e32 v186, v143
	v_exp_f32_e32 v187, v144
	v_exp_f32_e32 v194, v145
	v_mfma_f32_32x32x16_bf16 v[106:121], v[244:247], v[158:161], v[34:49]
	v_exp_f32_e32 v195, v146
	v_exp_f32_e32 v196, v147
	v_exp_f32_e32 v197, v148
	v_exp_f32_e32 v198, v149
	v_exp_f32_e32 v146, v150
	v_exp_f32_e32 v147, v151
	v_exp_f32_e32 v148, v152
	v_exp_f32_e32 v149, v153
	s_waitcnt lgkmcnt(1)
	v_mfma_f32_32x32x16_bf16 v[122:137], v[68:71], v[154:157], v[122:137]
	v_exp_f32_e32 v150, v82
	v_exp_f32_e32 v151, v83
	v_exp_f32_e32 v152, v84
	v_exp_f32_e32 v153, v85
	v_exp_f32_e32 v199, v86
	v_exp_f32_e32 v200, v87
	v_exp_f32_e32 v201, v88
	s_waitcnt lgkmcnt(0)
	v_mfma_f32_32x32x16_bf16 v[106:121], v[72:75], v[154:157], v[106:121]
	v_exp_f32_e32 v206, v93
	v_exp_f32_e32 v207, v94
	v_exp_f32_e32 v208, v95
	v_exp_f32_e32 v209, v96
	v_exp_f32_e32 v210, v97
	s_cmp_gt_i32 s25, 2
	s_cselect_b32 s28, -3, 2
	s_add_i32 s28, s28, s25
	s_mulk_i32 s28, 0x2400
	v_add_u32_e32 v88, s27, v163
	s_min_u32 s27, s23, s13
	v_add_u32_e32 v51, s28, v182
	s_lshl_b32 s92, s27, 13
	s_waitcnt vmcnt(3)
	ds_write_b128 v182, v[98:101] offset:18432
	s_waitcnt vmcnt(2)
	ds_write_b128 v51, v[102:105] offset:36864
	v_add_f32_e32 v1, v1, v50
	s_add_u32 vcc_lo, s100, s92
	s_addc_u32 vcc_hi, s101, 0
	global_load_dwordx4 v[138:141], v248, vcc
	s_lshl_b32 s92, s26, 7
	s_add_u32 vcc_lo, s98, s92
	s_addc_u32 vcc_hi, s99, 0
	global_load_dwordx4 v[142:145], v249, vcc
	ds_read_b128 v[240:243], v165 offset:9216
	ds_read_b128 v[244:247], v165 offset:13824
	ds_read_b128 v[60:63], v88 offset:41472
	ds_read_b128 v[64:67], v88 offset:36864
	ds_read_b128 v[68:71], v88 offset:36896
	ds_read_b128 v[72:75], v88 offset:41504
	ds_read_b128 v[76:79], v88 offset:36928
	ds_read_b128 v[80:83], v88 offset:41536
	ds_read_b128 v[84:87], v88 offset:36960
	ds_read_b128 v[88:91], v88 offset:41568
	s_setprio 1
	v_mov_b32_e32 v51, v122
	v_cvt_pk_bf16_f32 v92, v176, v177
	v_cvt_pk_bf16_f32 v93, v178, v179
	v_cvt_pk_bf16_f32 v94, v185, v186
	v_cvt_pk_bf16_f32 v95, v187, v194
	s_waitcnt lgkmcnt(6)
	s_nop 0
	v_mfma_f32_32x32x16_bf16 v[18:33], v[64:67], v[92:95], v[18:33]
	v_max3_f32 v51, v51, v123, v124
	v_max3_f32 v51, v51, v125, v126
	v_mov_b32_e32 v50, v176
	v_add_f32_e32 v50, v50, v177
	v_add_f32_e32 v50, v50, v178
	v_add_f32_e32 v50, v50, v179
	s_nop 0
	v_mfma_f32_32x32x16_bf16 v[2:17], v[60:63], v[92:95], v[2:17]
	v_cvt_pk_bf16_f32 v64, v195, v196
	v_cvt_pk_bf16_f32 v65, v197, v198
	v_cvt_pk_bf16_f32 v66, v146, v147
	v_cvt_pk_bf16_f32 v67, v148, v149
	v_max3_f32 v51, v51, v127, v128
	v_max3_f32 v51, v51, v129, v130
	v_add_f32_e32 v50, v50, v185
	v_add_f32_e32 v50, v50, v186
	v_add_f32_e32 v50, v50, v187
	v_add_f32_e32 v50, v50, v194
	s_waitcnt lgkmcnt(5)
	v_mfma_f32_32x32x16_bf16 v[18:33], v[68:71], v[64:67], v[18:33]
	v_max3_f32 v51, v51, v131, v132
	v_max3_f32 v51, v51, v133, v134
	v_add_f32_e32 v50, v50, v195
	v_add_f32_e32 v50, v50, v196
	v_add_f32_e32 v50, v50, v197
	v_add_f32_e32 v50, v50, v198
	s_waitcnt lgkmcnt(4)
	v_mfma_f32_32x32x16_bf16 v[2:17], v[72:75], v[64:67], v[2:17]
	v_cvt_pk_bf16_f32 v60, v150, v151
	v_cvt_pk_bf16_f32 v61, v152, v153
	v_cvt_pk_bf16_f32 v62, v199, v200
	v_cvt_pk_bf16_f32 v63, v201, v202
	v_max3_f32 v51, v51, v135, v136
	v_max3_f32 v51, v51, v137, v106
	v_add_f32_e32 v50, v50, v146
	v_add_f32_e32 v50, v50, v147
	v_add_f32_e32 v50, v50, v148
	v_add_f32_e32 v50, v50, v149
	s_waitcnt lgkmcnt(3)
	v_mfma_f32_32x32x16_bf16 v[18:33], v[76:79], v[60:63], v[18:33]
	v_max3_f32 v51, v51, v107, v108
	v_max3_f32 v51, v51, v109, v110
	v_add_f32_e32 v50, v50, v150
	v_add_f32_e32 v50, v50, v151
	v_add_f32_e32 v50, v50, v152
	v_add_f32_e32 v50, v50, v153
	s_waitcnt lgkmcnt(2)
	v_mfma_f32_32x32x16_bf16 v[2:17], v[80:83], v[60:63], v[2:17]
	v_cvt_pk_bf16_f32 v64, v203, v204
	v_cvt_pk_bf16_f32 v65, v205, v206
	v_cvt_pk_bf16_f32 v66, v207, v208
	v_cvt_pk_bf16_f32 v67, v209, v210
	v_max3_f32 v51, v51, v111, v112
	v_max3_f32 v51, v51, v113, v114
	v_add_f32_e32 v50, v50, v199
	v_add_f32_e32 v50, v50, v200
	v_add_f32_e32 v50, v50, v201
	v_add_f32_e32 v50, v50, v202
	s_waitcnt lgkmcnt(1)
	v_mfma_f32_32x32x16_bf16 v[18:33], v[84:87], v[64:67], v[18:33]
	v_max3_f32 v51, v51, v115, v116
	v_max3_f32 v51, v51, v117, v118
	v_add_f32_e32 v50, v50, v203
	v_add_f32_e32 v50, v50, v204
	v_add_f32_e32 v50, v50, v205
	v_add_f32_e32 v50, v50, v206
	s_waitcnt lgkmcnt(0)
	v_mfma_f32_32x32x16_bf16 v[2:17], v[88:91], v[64:67], v[2:17]
	v_max3_f32 v51, v51, v119, v120
	v_max3_f32 v51, v51, v121, v121
	v_add_f32_e32 v50, v50, v207
	v_add_f32_e32 v50, v50, v208
	v_add_f32_e32 v50, v50, v209
	v_add_f32_e32 v50, v50, v210
	s_setprio 0
	ds_read_b128 v[146:149], v165 offset:9248
	ds_read_b128 v[60:63], v165 offset:13856
	v_add_f32_e32 v50, v1, v50
	v_mov_b32_e32 v1, v51
	s_nop 1
	v_permlane32_swap_b32_e32 v51, v1
	v_max_f32_e32 v1, v1, v1
	v_max_f32_e32 v51, v51, v51
	v_max_f32_e32 v1, v51, v1
	v_cmp_lt_f32_e32 vcc, s52, v1
	s_cbranch_vccz .LBB0_643
	v_max_f32_e32 v1, v1, v1
	v_max_f32_e32 v68, 0, v1
	v_add_f32_e32 v183, v183, v68
	v_xor_b32_e32 v34, 0x80000000, v183
	v_pk_add_f32 v[122:123], v[122:123], v[68:69] op_sel_hi:[1,0] neg_lo:[0,1] neg_hi:[0,1]
	v_pk_add_f32 v[106:107], v[106:107], v[68:69] op_sel_hi:[1,0] neg_lo:[0,1] neg_hi:[0,1]
	v_pk_add_f32 v[124:125], v[124:125], v[68:69] op_sel_hi:[1,0] neg_lo:[0,1] neg_hi:[0,1]
	v_pk_add_f32 v[108:109], v[108:109], v[68:69] op_sel_hi:[1,0] neg_lo:[0,1] neg_hi:[0,1]
	v_pk_add_f32 v[126:127], v[126:127], v[68:69] op_sel_hi:[1,0] neg_lo:[0,1] neg_hi:[0,1]
	v_pk_add_f32 v[110:111], v[110:111], v[68:69] op_sel_hi:[1,0] neg_lo:[0,1] neg_hi:[0,1]
	v_pk_add_f32 v[128:129], v[128:129], v[68:69] op_sel_hi:[1,0] neg_lo:[0,1] neg_hi:[0,1]
	v_pk_add_f32 v[112:113], v[112:113], v[68:69] op_sel_hi:[1,0] neg_lo:[0,1] neg_hi:[0,1]
	v_pk_add_f32 v[130:131], v[130:131], v[68:69] op_sel_hi:[1,0] neg_lo:[0,1] neg_hi:[0,1]
	v_pk_add_f32 v[114:115], v[114:115], v[68:69] op_sel_hi:[1,0] neg_lo:[0,1] neg_hi:[0,1]
	v_pk_add_f32 v[132:133], v[132:133], v[68:69] op_sel_hi:[1,0] neg_lo:[0,1] neg_hi:[0,1]
	v_pk_add_f32 v[116:117], v[116:117], v[68:69] op_sel_hi:[1,0] neg_lo:[0,1] neg_hi:[0,1]
	v_pk_add_f32 v[134:135], v[134:135], v[68:69] op_sel_hi:[1,0] neg_lo:[0,1] neg_hi:[0,1]
	v_pk_add_f32 v[118:119], v[118:119], v[68:69] op_sel_hi:[1,0] neg_lo:[0,1] neg_hi:[0,1]
	v_pk_add_f32 v[136:137], v[136:137], v[68:69] op_sel_hi:[1,0] neg_lo:[0,1] neg_hi:[0,1]
	v_pk_add_f32 v[120:121], v[120:121], v[68:69] op_sel_hi:[1,0] neg_lo:[0,1] neg_hi:[0,1]
	v_exp_f32_e64 v68, -v68
	v_mov_b32_e32 v35, v34
	v_mov_b32_e32 v36, v34
	v_mov_b32_e32 v37, v34
	v_mov_b32_e32 v38, v34
	v_mov_b32_e32 v39, v34
	v_mov_b32_e32 v40, v34
	v_mov_b32_e32 v41, v34
	v_mov_b32_e32 v42, v34
	v_mov_b32_e32 v43, v34
	v_mov_b32_e32 v44, v34
	v_mov_b32_e32 v45, v34
	v_mov_b32_e32 v46, v34
	v_mov_b32_e32 v47, v34
	v_mov_b32_e32 v48, v34
	v_mov_b32_e32 v49, v34
	s_nop 11
	v_pk_mul_f32 v[32:33], v[32:33], v[68:69] op_sel_hi:[1,0]
	v_pk_mul_f32 v[30:31], v[30:31], v[68:69] op_sel_hi:[1,0]
	v_pk_mul_f32 v[28:29], v[28:29], v[68:69] op_sel_hi:[1,0]
	v_pk_mul_f32 v[26:27], v[26:27], v[68:69] op_sel_hi:[1,0]
	v_pk_mul_f32 v[24:25], v[24:25], v[68:69] op_sel_hi:[1,0]
	v_pk_mul_f32 v[22:23], v[22:23], v[68:69] op_sel_hi:[1,0]
	v_pk_mul_f32 v[20:21], v[20:21], v[68:69] op_sel_hi:[1,0]
	v_pk_mul_f32 v[18:19], v[18:19], v[68:69] op_sel_hi:[1,0]
	v_pk_mul_f32 v[16:17], v[16:17], v[68:69] op_sel_hi:[1,0]
	v_pk_mul_f32 v[14:15], v[14:15], v[68:69] op_sel_hi:[1,0]
	v_pk_mul_f32 v[12:13], v[12:13], v[68:69] op_sel_hi:[1,0]
	v_pk_mul_f32 v[10:11], v[10:11], v[68:69] op_sel_hi:[1,0]
	v_pk_mul_f32 v[8:9], v[8:9], v[68:69] op_sel_hi:[1,0]
	v_pk_mul_f32 v[6:7], v[6:7], v[68:69] op_sel_hi:[1,0]
	v_pk_mul_f32 v[4:5], v[4:5], v[68:69] op_sel_hi:[1,0]
	v_pk_mul_f32 v[2:3], v[2:3], v[68:69] op_sel_hi:[1,0]
	v_mul_f32_e32 v50, v50, v68

.LBB0_661:
	v_lshl_add_u64 v[164:165], v[204:205], 0, v[200:201]
	s_mov_b32 s26, 0x1da8a000
	v_add_co_u32_e32 v2, vcc, s26, v164
	v_lshl_add_u64 v[6:7], v[202:203], 0, v[200:201]
	s_nop 0
	v_addc_co_u32_e32 v3, vcc, 0, v165, vcc
	s_mov_b32 s26, 0x1e2a0000
	v_add_co_u32_e32 v14, vcc, s26, v6
	s_nop 0
	v_addc_co_u32_e32 v15, vcc, 0, v7, vcc
	global_load_dwordx4 v[2:5], v[2:3], off
	s_mul_i32 s28, s27, 0x2400
	global_load_dwordx4 v[6:9], v[14:15], off offset:512
	s_add_i32 s26, s13, -7
	s_add_i32 s29, s28, 0xffffdc00
	s_cmp_lg_u32 s27, 0
	s_cselect_b32 s29, s29, 0x9000
	v_add_u32_e32 v1, s29, v195
	ds_read_b128 v[10:13], v1 offset:36864
	ds_read_b128 v[66:69], v1 offset:36896
	ds_read_b128 v[70:73], v1 offset:41472
	ds_read_b128 v[74:77], v1 offset:41504
	ds_read_b128 v[128:131], v1 offset:36928
	ds_read_b128 v[132:135], v1 offset:36960
	ds_read_b128 v[148:151], v1 offset:41536
	ds_read_b128 v[160:163], v1 offset:41568
	s_setprio 3
	v_cvt_pk_bf16_f32 v210, v116, v117
	v_cvt_pk_bf16_f32 v211, v118, v119
	v_cvt_pk_bf16_f32 v212, v112, v113
	v_cvt_pk_bf16_f32 v213, v114, v115
	s_waitcnt lgkmcnt(7)
	s_nop 0
	v_mfma_f32_32x32x16_bf16 v[16:31], v[10:13], v[210:213], v[16:31]
	v_mov_b32_e32 v1, v116
	v_add_f32_e32 v1, v1, v117
	v_add_f32_e32 v1, v1, v118
	v_add_f32_e32 v1, v1, v119
	v_exp_f32_e32 v166, v96
	v_exp_f32_e32 v167, v97
	s_waitcnt lgkmcnt(5)
	v_mfma_f32_32x32x16_bf16 v[32:47], v[70:73], v[210:213], v[32:47]
	v_cvt_pk_bf16_f32 v10, v187, v186
	v_cvt_pk_bf16_f32 v11, v185, v184
	v_cvt_pk_bf16_f32 v12, v147, v146
	v_cvt_pk_bf16_f32 v13, v145, v144
	v_add_f32_e32 v1, v1, v112
	v_add_f32_e32 v1, v1, v113
	v_add_f32_e32 v1, v1, v114
	v_add_f32_e32 v1, v1, v115
	s_nop 0
	v_mfma_f32_32x32x16_bf16 v[16:31], v[66:69], v[10:13], v[16:31]
	v_add_f32_e32 v1, v1, v187
	v_add_f32_e32 v1, v1, v186
	v_add_f32_e32 v1, v1, v185
	v_add_f32_e32 v1, v1, v184
	v_exp_f32_e32 v210, v98
	v_exp_f32_e32 v211, v99
	s_waitcnt lgkmcnt(4)
	v_mfma_f32_32x32x16_bf16 v[32:47], v[74:77], v[10:13], v[32:47]
	v_cvt_pk_bf16_f32 v66, v143, v142
	v_cvt_pk_bf16_f32 v67, v141, v140
	v_cvt_pk_bf16_f32 v68, v139, v138
	v_cvt_pk_bf16_f32 v69, v137, v136
	v_add_f32_e32 v1, v1, v147
	v_add_f32_e32 v1, v1, v146
	v_add_f32_e32 v1, v1, v145
	v_add_f32_e32 v1, v1, v144
	s_waitcnt lgkmcnt(3)
	v_mfma_f32_32x32x16_bf16 v[16:31], v[128:131], v[66:69], v[16:31]
	v_add_f32_e32 v1, v1, v143
	v_add_f32_e32 v1, v1, v142
	v_add_f32_e32 v1, v1, v141
	v_add_f32_e32 v1, v1, v140
	v_exp_f32_e32 v212, v100
	v_exp_f32_e32 v213, v101
	s_waitcnt lgkmcnt(1)
	v_mfma_f32_32x32x16_bf16 v[32:47], v[148:151], v[66:69], v[32:47]
	v_cvt_pk_bf16_f32 v10, v123, v122
	v_cvt_pk_bf16_f32 v11, v121, v120
	v_cvt_pk_bf16_f32 v12, v127, v126
	v_cvt_pk_bf16_f32 v13, v125, v124
	v_add_f32_e32 v1, v1, v139
	v_add_f32_e32 v1, v1, v138
	v_add_f32_e32 v1, v1, v137
	v_add_f32_e32 v1, v1, v136
	s_nop 0
	v_mfma_f32_32x32x16_bf16 v[16:31], v[132:135], v[10:13], v[16:31]
	v_add_f32_e32 v1, v1, v123
	v_add_f32_e32 v1, v1, v122
	v_add_f32_e32 v1, v1, v121
	v_add_f32_e32 v1, v1, v120
	v_exp_f32_e32 v214, v102
	v_exp_f32_e32 v215, v103
	s_waitcnt lgkmcnt(0)
	v_mfma_f32_32x32x16_bf16 v[32:47], v[160:163], v[10:13], v[32:47]
	v_add_f32_e32 v1, v1, v127
	v_add_f32_e32 v1, v1, v126
	v_add_f32_e32 v1, v1, v125
	v_add_f32_e32 v1, v1, v124
	s_setprio 2
	s_waitcnt lgkmcnt(0)
	s_barrier
	ds_read_b128 v[240:243], v195 offset:18432
	ds_read_b128 v[244:247], v195 offset:23040
	ds_read_b128 v[66:69], v195 offset:18464
	ds_read_b128 v[74:77], v195 offset:23072
	ds_read_b128 v[144:147], v195 offset:18496
	ds_read_b128 v[148:151], v195 offset:18528
	ds_read_b128 v[160:163], v195 offset:23104
	ds_read_b128 v[184:187], v195 offset:23136
	s_waitcnt lgkmcnt(6)
	v_mfma_f32_32x32x16_bf16 v[128:143], v[240:243], v[180:183], v[48:63]
	s_waitcnt lgkmcnt(5)
	v_mfma_f32_32x32x16_bf16 v[112:127], v[244:247], v[180:183], v[48:63]
	v_mfma_f32_32x32x16_bf16 v[128:143], v[66:69], v[176:179], v[128:143]
	v_exp_f32_e32 v100, v104
	v_exp_f32_e32 v101, v105
	v_exp_f32_e32 v102, v106
	v_exp_f32_e32 v103, v107
	s_waitcnt lgkmcnt(4)
	v_mfma_f32_32x32x16_bf16 v[112:127], v[74:77], v[176:179], v[112:127]
	v_exp_f32_e32 v104, v108
	v_exp_f32_e32 v105, v109
	v_exp_f32_e32 v106, v110
	v_exp_f32_e32 v107, v111
	s_waitcnt lgkmcnt(3)
	v_mfma_f32_32x32x16_bf16 v[128:143], v[144:147], v[172:175], v[128:143]
	v_exp_f32_e32 v108, v80
	v_exp_f32_e32 v109, v81
	v_exp_f32_e32 v110, v82
	v_exp_f32_e32 v111, v83
	s_waitcnt lgkmcnt(1)
	v_mfma_f32_32x32x16_bf16 v[112:127], v[160:163], v[172:175], v[112:127]
	v_exp_f32_e32 v144, v84
	v_exp_f32_e32 v145, v85
	v_exp_f32_e32 v146, v86
	v_exp_f32_e32 v147, v87
	v_mfma_f32_32x32x16_bf16 v[128:143], v[148:151], v[168:171], v[128:143]
	v_exp_f32_e32 v216, v88
	v_exp_f32_e32 v217, v89
	v_exp_f32_e32 v218, v90
	v_exp_f32_e32 v219, v91
	s_waitcnt lgkmcnt(0)
	v_mfma_f32_32x32x16_bf16 v[112:127], v[184:187], v[168:171], v[112:127]
	v_exp_f32_e32 v148, v92
	v_exp_f32_e32 v149, v93
	v_exp_f32_e32 v150, v94
	v_exp_f32_e32 v151, v95
	s_cmp_gt_i32 s27, 2
	s_cselect_b32 s29, -3, 2
	s_add_i32 s29, s29, s27
	v_add_u32_e32 v92, s28, v195
	s_add_i32 s28, s13, -6
	s_mulk_i32 s29, 0x2400
	s_min_u32 s28, s28, s12
	v_add_u32_e32 v10, s29, v208
	s_min_u32 s26, s26, s12
	s_lshl_b32 s92, s28, 13
	s_waitcnt vmcnt(3)
	ds_write_b128 v208, v[152:155]
	s_waitcnt vmcnt(2)
	ds_write_b128 v10, v[156:159] offset:36864
	s_add_u32 vcc_lo, s100, s92
	s_addc_u32 vcc_hi, s101, 0
	global_load_dwordx4 v[10:13], v248, vcc
	s_lshl_b32 s92, s26, 7
	v_add_f32_e32 v1, v64, v1
	s_add_u32 vcc_lo, s98, s92
	s_addc_u32 vcc_hi, s99, 0
	global_load_dwordx4 v[160:163], v249, vcc
	s_add_i32 s29, s27, 1
	ds_read_b128 v[240:243], v195 offset:27648
	ds_read_b128 v[244:247], v195 offset:32256
	ds_read_b128 v[64:67], v92 offset:41472
	ds_read_b128 v[68:71], v92 offset:36864
	ds_read_b128 v[72:75], v92 offset:36896
	ds_read_b128 v[76:79], v92 offset:41504
	ds_read_b128 v[80:83], v92 offset:36928
	ds_read_b128 v[84:87], v92 offset:41536
	ds_read_b128 v[88:91], v92 offset:36960
	ds_read_b128 v[92:95], v92 offset:41568
	s_setprio 1
	v_cvt_pk_bf16_f32 v96, v166, v167
	v_cvt_pk_bf16_f32 v97, v210, v211
	v_cvt_pk_bf16_f32 v98, v212, v213
	v_cvt_pk_bf16_f32 v99, v214, v215
	s_waitcnt lgkmcnt(6)
	s_nop 0
	v_mfma_f32_32x32x16_bf16 v[16:31], v[68:71], v[96:99], v[16:31]
	v_mov_b32_e32 v184, v166
	v_add_f32_e32 v184, v184, v167
	v_add_f32_e32 v184, v184, v210
	v_add_f32_e32 v184, v184, v211
	v_exp_f32_e32 v166, v128
	v_exp_f32_e32 v167, v129
	s_nop 0
	v_mfma_f32_32x32x16_bf16 v[32:47], v[64:67], v[96:99], v[32:47]
	v_cvt_pk_bf16_f32 v68, v100, v101
	v_cvt_pk_bf16_f32 v69, v102, v103
	v_cvt_pk_bf16_f32 v70, v104, v105
	v_cvt_pk_bf16_f32 v71, v106, v107
	v_add_f32_e32 v184, v184, v212
	v_add_f32_e32 v184, v184, v213
	v_add_f32_e32 v184, v184, v214
	v_add_f32_e32 v184, v184, v215
	s_waitcnt lgkmcnt(5)
	v_mfma_f32_32x32x16_bf16 v[16:31], v[72:75], v[68:71], v[16:31]
	v_add_f32_e32 v184, v184, v100
	v_add_f32_e32 v184, v184, v101
	v_add_f32_e32 v184, v184, v102
	v_add_f32_e32 v184, v184, v103
	v_exp_f32_e32 v185, v130
	v_exp_f32_e32 v186, v131
	s_waitcnt lgkmcnt(4)
	v_mfma_f32_32x32x16_bf16 v[32:47], v[76:79], v[68:71], v[32:47]
	v_cvt_pk_bf16_f32 v64, v108, v109
	v_cvt_pk_bf16_f32 v65, v110, v111
	v_cvt_pk_bf16_f32 v66, v144, v145
	v_cvt_pk_bf16_f32 v67, v146, v147
	v_add_f32_e32 v184, v184, v104
	v_add_f32_e32 v184, v184, v105
	v_add_f32_e32 v184, v184, v106
	v_add_f32_e32 v184, v184, v107
	s_waitcnt lgkmcnt(3)
	v_mfma_f32_32x32x16_bf16 v[16:31], v[80:83], v[64:67], v[16:31]
	v_add_f32_e32 v184, v184, v108
	v_add_f32_e32 v184, v184, v109
	v_add_f32_e32 v184, v184, v110
	v_add_f32_e32 v184, v184, v111
	v_exp_f32_e32 v128, v132
	v_exp_f32_e32 v129, v133
	s_waitcnt lgkmcnt(2)
	v_mfma_f32_32x32x16_bf16 v[32:47], v[84:87], v[64:67], v[32:47]
	v_cvt_pk_bf16_f32 v68, v216, v217
	v_cvt_pk_bf16_f32 v69, v218, v219
	v_cvt_pk_bf16_f32 v70, v148, v149
	v_cvt_pk_bf16_f32 v71, v150, v151
	v_add_f32_e32 v184, v184, v144
	v_add_f32_e32 v184, v184, v145
	v_add_f32_e32 v184, v184, v146
	v_add_f32_e32 v184, v184, v147
	s_waitcnt lgkmcnt(1)
	v_mfma_f32_32x32x16_bf16 v[16:31], v[88:91], v[68:71], v[16:31]
	v_add_f32_e32 v184, v184, v216
	v_add_f32_e32 v184, v184, v217
	v_add_f32_e32 v184, v184, v218
	v_add_f32_e32 v184, v184, v219
	v_exp_f32_e32 v130, v134
	v_exp_f32_e32 v131, v135
	s_waitcnt lgkmcnt(0)
	v_mfma_f32_32x32x16_bf16 v[32:47], v[92:95], v[68:71], v[32:47]
	v_add_f32_e32 v184, v184, v148
	v_add_f32_e32 v184, v184, v149
	v_add_f32_e32 v184, v184, v150
	v_add_f32_e32 v184, v184, v151
	s_setprio 0
	ds_read_b128 v[68:71], v195 offset:27680
	ds_read_b128 v[76:79], v195 offset:32288
	ds_read_b128 v[80:83], v195 offset:27712
	ds_read_b128 v[84:87], v195 offset:27744
	ds_read_b128 v[88:91], v195 offset:32320
	ds_read_b128 v[92:95], v195 offset:32352
	s_cmp_lg_u32 s27, 4
	s_cselect_b32 s26, s29, 0
	s_waitcnt lgkmcnt(6)
	v_mfma_f32_32x32x16_bf16 v[144:159], v[240:243], v[180:183], v[48:63]
	s_waitcnt lgkmcnt(5)
	v_mfma_f32_32x32x16_bf16 v[96:111], v[244:247], v[180:183], v[48:63]
	v_mfma_f32_32x32x16_bf16 v[144:159], v[68:71], v[176:179], v[144:159]
	v_exp_f32_e32 v132, v136
	v_exp_f32_e32 v133, v137
	v_exp_f32_e32 v134, v138
	v_exp_f32_e32 v135, v139
	s_waitcnt lgkmcnt(4)
	v_mfma_f32_32x32x16_bf16 v[96:111], v[76:79], v[176:179], v[96:111]
	v_exp_f32_e32 v136, v140
	v_exp_f32_e32 v137, v141
	v_exp_f32_e32 v138, v142
	v_exp_f32_e32 v139, v143
	s_waitcnt lgkmcnt(3)
	v_mfma_f32_32x32x16_bf16 v[144:159], v[80:83], v[172:175], v[144:159]
	v_exp_f32_e32 v140, v112
	v_exp_f32_e32 v141, v113
	v_exp_f32_e32 v142, v114
	v_exp_f32_e32 v143, v115
	s_waitcnt lgkmcnt(1)
	v_mfma_f32_32x32x16_bf16 v[96:111], v[88:91], v[172:175], v[96:111]
	v_exp_f32_e32 v187, v116
	v_exp_f32_e32 v210, v117
	v_exp_f32_e32 v211, v118
	v_exp_f32_e32 v212, v119
	v_mfma_f32_32x32x16_bf16 v[144:159], v[84:87], v[168:171], v[144:159]
	v_exp_f32_e32 v116, v120
	v_exp_f32_e32 v117, v121
	v_exp_f32_e32 v118, v122
	v_exp_f32_e32 v119, v123
	s_waitcnt lgkmcnt(0)
	v_mfma_f32_32x32x16_bf16 v[96:111], v[92:95], v[168:171], v[96:111]
	v_exp_f32_e32 v120, v124
	v_exp_f32_e32 v121, v125
	v_exp_f32_e32 v122, v126
	v_exp_f32_e32 v123, v127
	s_cmp_gt_i32 s26, 2
	s_cselect_b32 s27, -3, 2
	s_add_i32 s27, s27, s26
	s_mulk_i32 s27, 0x2400
	s_waitcnt vmcnt(3)
	ds_write_b128 v208, v[2:5] offset:9216
	v_add_u32_e32 v2, s27, v208
	s_add_i32 s27, s26, 1
	s_cmp_lg_u32 s26, 4
	s_cselect_b32 s26, s27, 0
	s_add_i32 s27, s13, -5
	s_min_u32 s27, s27, s12
	s_lshl_b32 s92, s27, 13
	s_waitcnt vmcnt(2)
	ds_write_b128 v2, v[6:9] offset:36864
	s_add_u32 vcc_lo, s100, s92
	s_addc_u32 vcc_hi, s101, 0
	global_load_dwordx4 v[6:9], v248, vcc
	s_lshl_b32 s92, s28, 7
	s_add_u32 vcc_lo, s98, s92
	s_addc_u32 vcc_hi, s99, 0
	global_load_dwordx4 v[2:5], v249, vcc
	s_nop 0
	s_mul_i32 s28, s26, 0x2400
	s_add_i32 s29, s28, 0xffffdc00
	s_cmp_lg_u32 s26, 0
	s_cselect_b32 s29, s29, 0x9000
	v_add_u32_e32 v92, s29, v195
	ds_read_b128 v[64:67], v92 offset:36864
	ds_read_b128 v[68:71], v92 offset:36896
	ds_read_b128 v[72:75], v92 offset:41472
	ds_read_b128 v[76:79], v92 offset:41504
	ds_read_b128 v[80:83], v92 offset:36928
	ds_read_b128 v[84:87], v92 offset:36960
	ds_read_b128 v[88:91], v92 offset:41536
	ds_read_b128 v[92:95], v92 offset:41568
	s_setprio 3
	v_cvt_pk_bf16_f32 v112, v166, v167
	v_cvt_pk_bf16_f32 v113, v185, v186
	v_cvt_pk_bf16_f32 v114, v128, v129
	v_cvt_pk_bf16_f32 v115, v130, v131
	s_waitcnt lgkmcnt(7)
	s_nop 0
	v_mfma_f32_32x32x16_bf16 v[16:31], v[64:67], v[112:115], v[16:31]
	v_mov_b32_e32 v213, v166
	v_add_f32_e32 v213, v213, v167
	v_add_f32_e32 v213, v213, v185
	v_add_f32_e32 v213, v213, v186
	v_exp_f32_e32 v166, v100
	v_exp_f32_e32 v167, v101
	s_waitcnt lgkmcnt(5)
	v_mfma_f32_32x32x16_bf16 v[32:47], v[72:75], v[112:115], v[32:47]
	v_cvt_pk_bf16_f32 v64, v132, v133
	v_cvt_pk_bf16_f32 v65, v134, v135
	v_cvt_pk_bf16_f32 v66, v136, v137
	v_cvt_pk_bf16_f32 v67, v138, v139
	v_add_f32_e32 v213, v213, v128
	v_add_f32_e32 v213, v213, v129
	v_add_f32_e32 v213, v213, v130
	v_add_f32_e32 v213, v213, v131
	s_nop 0
	v_mfma_f32_32x32x16_bf16 v[16:31], v[68:71], v[64:67], v[16:31]
	v_add_f32_e32 v213, v213, v132
	v_add_f32_e32 v213, v213, v133
	v_add_f32_e32 v213, v213, v134
	v_add_f32_e32 v213, v213, v135
	v_exp_f32_e32 v185, v103
	v_exp_f32_e32 v186, v104
	s_waitcnt lgkmcnt(4)
	v_mfma_f32_32x32x16_bf16 v[32:47], v[76:79], v[64:67], v[32:47]
	v_cvt_pk_bf16_f32 v68, v140, v141
	v_cvt_pk_bf16_f32 v69, v142, v143
	v_cvt_pk_bf16_f32 v70, v187, v210
	v_cvt_pk_bf16_f32 v71, v211, v212
	v_add_f32_e32 v213, v213, v136
	v_add_f32_e32 v213, v213, v137
	v_add_f32_e32 v213, v213, v138
	v_add_f32_e32 v213, v213, v139
	s_waitcnt lgkmcnt(3)
	v_mfma_f32_32x32x16_bf16 v[16:31], v[80:83], v[68:71], v[16:31]
	v_add_f32_e32 v213, v213, v140
	v_add_f32_e32 v213, v213, v141
	v_add_f32_e32 v213, v213, v142
	v_add_f32_e32 v213, v213, v143
	v_exp_f32_e32 v140, v144
	v_exp_f32_e32 v141, v145
	s_waitcnt lgkmcnt(1)
	v_mfma_f32_32x32x16_bf16 v[32:47], v[88:91], v[68:71], v[32:47]
	v_cvt_pk_bf16_f32 v64, v116, v117
	v_cvt_pk_bf16_f32 v65, v118, v119
	v_cvt_pk_bf16_f32 v66, v120, v121
	v_cvt_pk_bf16_f32 v67, v122, v123
	v_add_f32_e32 v213, v213, v187
	v_add_f32_e32 v213, v213, v210
	v_add_f32_e32 v213, v213, v211
	v_add_f32_e32 v213, v213, v212
	s_nop 0
	v_mfma_f32_32x32x16_bf16 v[16:31], v[84:87], v[64:67], v[16:31]
	v_add_f32_e32 v213, v213, v116
	v_add_f32_e32 v213, v213, v117
	v_add_f32_e32 v213, v213, v118
	v_add_f32_e32 v213, v213, v119
	v_exp_f32_e32 v142, v146
	v_exp_f32_e32 v143, v147
	s_waitcnt lgkmcnt(0)
	v_mfma_f32_32x32x16_bf16 v[32:47], v[92:95], v[64:67], v[32:47]
	v_add_f32_e32 v213, v213, v120
	v_add_f32_e32 v213, v213, v121
	v_add_f32_e32 v213, v213, v122
	v_add_f32_e32 v213, v213, v123
	s_setprio 2
	s_waitcnt lgkmcnt(0)
	s_barrier
	ds_read_b128 v[240:243], v195
	ds_read_b128 v[244:247], v195 offset:4608
	ds_read_b128 v[116:119], v195 offset:32
	ds_read_b128 v[120:123], v195 offset:4640
	ds_read_b128 v[124:127], v195 offset:64
	ds_read_b128 v[128:131], v195 offset:4672
	ds_read_b128 v[132:135], v195 offset:96
	ds_read_b128 v[136:139], v195 offset:4704
	v_add_f32_e32 v1, v1, v184
	s_waitcnt lgkmcnt(6)
	v_mfma_f32_32x32x16_bf16 v[80:95], v[240:243], v[180:183], v[48:63]
	v_mfma_f32_32x32x16_bf16 v[64:79], v[244:247], v[180:183], v[48:63]
	v_exp_f32_e32 v144, v148
	v_exp_f32_e32 v145, v149
	v_exp_f32_e32 v146, v150
	v_exp_f32_e32 v147, v151
	s_waitcnt lgkmcnt(5)
	v_mfma_f32_32x32x16_bf16 v[80:95], v[116:119], v[176:179], v[80:95]
	v_exp_f32_e32 v148, v152
	v_exp_f32_e32 v149, v153
	v_exp_f32_e32 v150, v154
	v_exp_f32_e32 v151, v155
	s_waitcnt lgkmcnt(4)
	v_mfma_f32_32x32x16_bf16 v[64:79], v[120:123], v[176:179], v[64:79]
	v_exp_f32_e32 v152, v156
	v_exp_f32_e32 v153, v157
	v_exp_f32_e32 v154, v158
	v_exp_f32_e32 v155, v159
	s_waitcnt lgkmcnt(3)
	v_mfma_f32_32x32x16_bf16 v[80:95], v[124:127], v[172:175], v[80:95]
	v_exp_f32_e32 v156, v96
	v_exp_f32_e32 v157, v97
	v_exp_f32_e32 v158, v98
	v_exp_f32_e32 v159, v99
	s_waitcnt lgkmcnt(2)
	v_mfma_f32_32x32x16_bf16 v[64:79], v[128:131], v[172:175], v[64:79]
	v_exp_f32_e32 v184, v102
	s_waitcnt lgkmcnt(1)
	v_mfma_f32_32x32x16_bf16 v[80:95], v[132:135], v[168:171], v[80:95]
	v_exp_f32_e32 v187, v105
	v_exp_f32_e32 v210, v106
	v_exp_f32_e32 v211, v107
	s_waitcnt lgkmcnt(0)
	v_mfma_f32_32x32x16_bf16 v[64:79], v[136:139], v[168:171], v[64:79]
	v_exp_f32_e32 v212, v108
	v_exp_f32_e32 v214, v109
	v_exp_f32_e32 v215, v110
	v_exp_f32_e32 v216, v111
	s_cmp_gt_i32 s26, 2
	s_cselect_b32 s29, -3, 2
	s_add_i32 s29, s29, s26
	s_mulk_i32 s29, 0x2400
	s_waitcnt vmcnt(3)
	ds_write_b128 v208, v[10:13] offset:18432
	v_add_u32_e32 v10, s29, v208
	s_mov_b32 s29, 0x1da90000
	s_waitcnt vmcnt(2)
	ds_write_b128 v10, v[160:163] offset:36864
	v_add_co_u32_e32 v10, vcc, s29, v164
	s_lshl_b32 s92, s27, 7
	s_nop 0
	v_addc_co_u32_e32 v11, vcc, 0, v165, vcc
	global_load_dwordx4 v[128:131], v[10:11], off
	s_add_u32 vcc_lo, s98, s92
	s_addc_u32 vcc_hi, s99, 0
	global_load_dwordx4 v[10:13], v249, vcc
	v_add_u32_e32 v124, s28, v195
	ds_read_b128 v[240:243], v195 offset:9216
	ds_read_b128 v[244:247], v195 offset:13824
	ds_read_b128 v[96:99], v124 offset:41472
	ds_read_b128 v[100:103], v124 offset:36864
	ds_read_b128 v[104:107], v124 offset:36896
	ds_read_b128 v[108:111], v124 offset:41504
	ds_read_b128 v[112:115], v124 offset:36928
	ds_read_b128 v[116:119], v124 offset:41536
	ds_read_b128 v[120:123], v124 offset:36960
	ds_read_b128 v[124:127], v124 offset:41568
	v_add_f32_e32 v1, v1, v213
	s_add_i32 s28, s26, 1
	s_setprio 1
	v_cvt_pk_bf16_f32 v132, v140, v141
	v_cvt_pk_bf16_f32 v133, v142, v143
	v_cvt_pk_bf16_f32 v134, v144, v145
	v_cvt_pk_bf16_f32 v135, v146, v147
	s_waitcnt lgkmcnt(6)
	s_nop 0
	v_mfma_f32_32x32x16_bf16 v[16:31], v[100:103], v[132:135], v[16:31]
	v_mov_b32_e32 v160, v140
	v_add_f32_e32 v160, v160, v141
	v_add_f32_e32 v160, v160, v142
	v_add_f32_e32 v160, v160, v143
	v_exp_f32_e32 v161, v80
	v_exp_f32_e32 v162, v81
	s_nop 0
	v_mfma_f32_32x32x16_bf16 v[32:47], v[96:99], v[132:135], v[32:47]
	v_cvt_pk_bf16_f32 v100, v148, v149
	v_cvt_pk_bf16_f32 v101, v150, v151
	v_cvt_pk_bf16_f32 v102, v152, v153
	v_cvt_pk_bf16_f32 v103, v154, v155
	v_add_f32_e32 v160, v160, v144
	v_add_f32_e32 v160, v160, v145
	v_add_f32_e32 v160, v160, v146
	v_add_f32_e32 v160, v160, v147
	s_waitcnt lgkmcnt(5)
	v_mfma_f32_32x32x16_bf16 v[16:31], v[104:107], v[100:103], v[16:31]
	v_add_f32_e32 v160, v160, v148
	v_add_f32_e32 v160, v160, v149
	v_add_f32_e32 v160, v160, v150
	v_add_f32_e32 v160, v160, v151
	v_exp_f32_e32 v163, v82
	v_exp_f32_e32 v164, v83
	s_waitcnt lgkmcnt(4)
	v_mfma_f32_32x32x16_bf16 v[32:47], v[108:111], v[100:103], v[32:47]
	v_cvt_pk_bf16_f32 v96, v156, v157
	v_cvt_pk_bf16_f32 v97, v158, v159
	v_cvt_pk_bf16_f32 v98, v166, v167
	v_cvt_pk_bf16_f32 v99, v184, v185
	v_add_f32_e32 v160, v160, v152
	v_add_f32_e32 v160, v160, v153
	v_add_f32_e32 v160, v160, v154
	v_add_f32_e32 v160, v160, v155
	s_waitcnt lgkmcnt(3)
	v_mfma_f32_32x32x16_bf16 v[16:31], v[112:115], v[96:99], v[16:31]
	v_add_f32_e32 v160, v160, v156
	v_add_f32_e32 v160, v160, v157
	v_add_f32_e32 v160, v160, v158
	v_add_f32_e32 v160, v160, v159
	v_exp_f32_e32 v165, v84
	v_exp_f32_e32 v136, v88
	s_waitcnt lgkmcnt(2)
	v_mfma_f32_32x32x16_bf16 v[32:47], v[116:119], v[96:99], v[32:47]
	v_cvt_pk_bf16_f32 v100, v186, v187
	v_cvt_pk_bf16_f32 v101, v210, v211
	v_cvt_pk_bf16_f32 v102, v212, v214
	v_cvt_pk_bf16_f32 v103, v215, v216
	v_add_f32_e32 v160, v160, v166
	v_add_f32_e32 v160, v160, v167
	v_add_f32_e32 v160, v160, v184
	v_add_f32_e32 v160, v160, v185
	s_waitcnt lgkmcnt(1)
	v_mfma_f32_32x32x16_bf16 v[16:31], v[120:123], v[100:103], v[16:31]
	v_add_f32_e32 v160, v160, v186
	v_add_f32_e32 v160, v160, v187
	v_add_f32_e32 v160, v160, v210
	v_add_f32_e32 v160, v160, v211
	v_exp_f32_e32 v166, v85
	v_exp_f32_e32 v167, v86
	s_waitcnt lgkmcnt(0)
	v_mfma_f32_32x32x16_bf16 v[32:47], v[124:127], v[100:103], v[32:47]
	v_add_f32_e32 v160, v160, v212
	v_add_f32_e32 v160, v160, v214
	v_add_f32_e32 v160, v160, v215
	v_add_f32_e32 v160, v160, v216
	s_setprio 0
	ds_read_b128 v[132:135], v195 offset:9248
	ds_read_b128 v[140:143], v195 offset:13856
	ds_read_b128 v[144:147], v195 offset:9280
	ds_read_b128 v[148:151], v195 offset:9312
	ds_read_b128 v[152:155], v195 offset:13888
	ds_read_b128 v[156:159], v195 offset:13920
	s_cmp_lg_u32 s26, 4
	s_cselect_b32 s26, s28, 0
	s_waitcnt lgkmcnt(6)
	v_mfma_f32_32x32x16_bf16 v[112:127], v[240:243], v[180:183], v[48:63]
	s_waitcnt lgkmcnt(5)
	v_mfma_f32_32x32x16_bf16 v[96:111], v[244:247], v[180:183], v[48:63]
	v_exp_f32_e32 v184, v87
	v_mfma_f32_32x32x16_bf16 v[112:127], v[132:135], v[176:179], v[112:127]
	v_exp_f32_e32 v137, v89
	v_exp_f32_e32 v138, v90
	v_exp_f32_e32 v139, v91
	s_waitcnt lgkmcnt(4)
	v_mfma_f32_32x32x16_bf16 v[96:111], v[140:143], v[176:179], v[96:111]
	v_exp_f32_e32 v185, v92
	v_exp_f32_e32 v186, v93
	v_exp_f32_e32 v187, v94
	v_exp_f32_e32 v210, v95
	s_waitcnt lgkmcnt(3)
	v_mfma_f32_32x32x16_bf16 v[112:127], v[144:147], v[172:175], v[112:127]
	v_exp_f32_e32 v140, v64
	v_exp_f32_e32 v141, v65
	v_exp_f32_e32 v142, v66
	v_exp_f32_e32 v143, v67
	s_waitcnt lgkmcnt(1)
	v_mfma_f32_32x32x16_bf16 v[96:111], v[152:155], v[172:175], v[96:111]
	v_exp_f32_e32 v144, v68
	v_exp_f32_e32 v145, v69
	v_exp_f32_e32 v146, v70
	v_exp_f32_e32 v147, v71
	v_mfma_f32_32x32x16_bf16 v[112:127], v[148:151], v[168:171], v[112:127]
	v_exp_f32_e32 v152, v72
	v_exp_f32_e32 v153, v73
	v_exp_f32_e32 v154, v74
	v_exp_f32_e32 v155, v75
	s_waitcnt lgkmcnt(0)
	v_mfma_f32_32x32x16_bf16 v[96:111], v[156:159], v[168:171], v[96:111]
	v_exp_f32_e32 v148, v76
	v_exp_f32_e32 v149, v77
	v_exp_f32_e32 v150, v78
	v_exp_f32_e32 v151, v79
	s_cmp_gt_i32 s26, 2
	s_cselect_b32 s27, -3, 2
	s_add_i32 s27, s27, s26
	s_mulk_i32 s27, 0x2400
	s_waitcnt vmcnt(3)
	ds_write_b128 v208, v[6:9] offset:27648
	v_add_u32_e32 v6, s27, v208
	s_add_i32 s27, s26, 1
	s_cmp_lg_u32 s26, 4
	s_cselect_b32 s27, s27, 0
	s_add_i32 s26, s13, -3
	s_min_u32 s28, s26, s12
	s_lshl_b32 s92, s28, 13
	s_waitcnt vmcnt(2)
	ds_write_b128 v6, v[2:5] offset:36864
	s_add_u32 vcc_lo, s100, s92
	s_addc_u32 vcc_hi, s101, 0
	global_load_dwordx4 v[6:9], v248, vcc
	s_nop 0
	global_load_dwordx4 v[2:5], v[14:15], off offset:1024
	s_mul_i32 s29, s27, 0x2400
	s_add_i32 s34, s29, 0xffffdc00
	s_cmp_lg_u32 s27, 0
	s_cselect_b32 s34, s34, 0x9000
	v_add_u32_e32 v14, s34, v195
	ds_read_b128 v[64:67], v14 offset:36864
	ds_read_b128 v[68:71], v14 offset:36896
	ds_read_b128 v[72:75], v14 offset:41472
	ds_read_b128 v[76:79], v14 offset:41504
	ds_read_b128 v[80:83], v14 offset:36928
	ds_read_b128 v[84:87], v14 offset:36960
	ds_read_b128 v[88:91], v14 offset:41536
	ds_read_b128 v[92:95], v14 offset:41568
	s_setprio 3
	v_cvt_pk_bf16_f32 v132, v161, v162
	v_cvt_pk_bf16_f32 v133, v163, v164
	v_cvt_pk_bf16_f32 v134, v165, v166
	v_cvt_pk_bf16_f32 v135, v167, v184
	s_waitcnt lgkmcnt(7)
	s_nop 0
	v_mfma_f32_32x32x16_bf16 v[16:31], v[64:67], v[132:135], v[16:31]
	v_mov_b32_e32 v14, v161
	v_add_f32_e32 v14, v14, v162
	v_add_f32_e32 v14, v14, v163
	v_add_f32_e32 v14, v14, v164
	v_exp_f32_e32 v161, v113
	v_exp_f32_e32 v162, v114
	s_waitcnt lgkmcnt(5)
	v_mfma_f32_32x32x16_bf16 v[32:47], v[72:75], v[132:135], v[32:47]
	v_cvt_pk_bf16_f32 v64, v136, v137
	v_cvt_pk_bf16_f32 v65, v138, v139
	v_cvt_pk_bf16_f32 v66, v185, v186
	v_cvt_pk_bf16_f32 v67, v187, v210
	v_add_f32_e32 v14, v14, v165
	v_add_f32_e32 v14, v14, v166
	v_add_f32_e32 v14, v14, v167
	v_add_f32_e32 v14, v14, v184
	s_nop 0
	v_mfma_f32_32x32x16_bf16 v[16:31], v[68:71], v[64:67], v[16:31]
	v_add_f32_e32 v14, v14, v136
	v_add_f32_e32 v14, v14, v137
	v_add_f32_e32 v14, v14, v138
	v_add_f32_e32 v14, v14, v139
	v_exp_f32_e32 v163, v115
	v_exp_f32_e32 v164, v116
	s_waitcnt lgkmcnt(4)
	v_mfma_f32_32x32x16_bf16 v[32:47], v[76:79], v[64:67], v[32:47]
	v_cvt_pk_bf16_f32 v68, v140, v141
	v_cvt_pk_bf16_f32 v69, v142, v143
	v_cvt_pk_bf16_f32 v70, v144, v145
	v_cvt_pk_bf16_f32 v71, v146, v147
	v_add_f32_e32 v14, v14, v185
	v_add_f32_e32 v14, v14, v186
	v_add_f32_e32 v14, v14, v187
	v_add_f32_e32 v14, v14, v210
	s_waitcnt lgkmcnt(3)
	v_mfma_f32_32x32x16_bf16 v[16:31], v[80:83], v[68:71], v[16:31]
	v_add_f32_e32 v14, v14, v140
	v_add_f32_e32 v14, v14, v141
	v_add_f32_e32 v14, v14, v142
	v_add_f32_e32 v14, v14, v143
	v_exp_f32_e32 v165, v117
	v_exp_f32_e32 v166, v118
	s_waitcnt lgkmcnt(1)
	v_mfma_f32_32x32x16_bf16 v[32:47], v[88:91], v[68:71], v[32:47]
	v_cvt_pk_bf16_f32 v64, v152, v153
	v_cvt_pk_bf16_f32 v65, v154, v155
	v_cvt_pk_bf16_f32 v66, v148, v149
	v_cvt_pk_bf16_f32 v67, v150, v151
	v_add_f32_e32 v14, v14, v144
	v_add_f32_e32 v14, v14, v145
	v_add_f32_e32 v14, v14, v146
	v_add_f32_e32 v14, v14, v147
	s_nop 0
	v_mfma_f32_32x32x16_bf16 v[16:31], v[84:87], v[64:67], v[16:31]
	v_add_f32_e32 v14, v14, v152
	v_add_f32_e32 v14, v14, v153
	v_add_f32_e32 v14, v14, v154
	v_add_f32_e32 v14, v14, v155
	v_exp_f32_e32 v167, v119
	v_exp_f32_e32 v184, v120
	s_waitcnt lgkmcnt(0)
	v_mfma_f32_32x32x16_bf16 v[32:47], v[92:95], v[64:67], v[32:47]
	v_add_f32_e32 v14, v14, v148
	v_add_f32_e32 v14, v14, v149
	v_add_f32_e32 v14, v14, v150
	v_add_f32_e32 v14, v14, v151
	s_setprio 2
	s_waitcnt lgkmcnt(0)
	s_barrier
	ds_read_b128 v[240:243], v195 offset:18432
	ds_read_b128 v[244:247], v195 offset:23040
	ds_read_b128 v[136:139], v195 offset:18464
	ds_read_b128 v[140:143], v195 offset:23072
	ds_read_b128 v[144:147], v195 offset:18496
	ds_read_b128 v[148:151], v195 offset:23104
	ds_read_b128 v[152:155], v195 offset:18528
	ds_read_b128 v[156:159], v195 offset:23136
	v_add_f32_e32 v1, v1, v160
	s_waitcnt lgkmcnt(6)
	v_mfma_f32_32x32x16_bf16 v[80:95], v[240:243], v[180:183], v[48:63]
	v_exp_f32_e32 v160, v112
	v_mfma_f32_32x32x16_bf16 v[64:79], v[244:247], v[180:183], v[48:63]
	s_waitcnt lgkmcnt(5)
	v_mfma_f32_32x32x16_bf16 v[80:95], v[136:139], v[176:179], v[80:95]
	v_exp_f32_e32 v185, v121
	v_exp_f32_e32 v186, v122
	v_exp_f32_e32 v187, v123
	s_waitcnt lgkmcnt(4)
	v_mfma_f32_32x32x16_bf16 v[64:79], v[140:143], v[176:179], v[64:79]
	v_exp_f32_e32 v136, v124
	v_exp_f32_e32 v137, v125
	v_exp_f32_e32 v138, v126
	v_exp_f32_e32 v139, v127
	s_waitcnt lgkmcnt(3)
	v_mfma_f32_32x32x16_bf16 v[80:95], v[144:147], v[172:175], v[80:95]
	v_exp_f32_e32 v140, v96
	v_exp_f32_e32 v141, v97
	v_exp_f32_e32 v142, v98
	v_exp_f32_e32 v143, v99
	s_waitcnt lgkmcnt(2)
	v_mfma_f32_32x32x16_bf16 v[64:79], v[148:151], v[172:175], v[64:79]
	v_exp_f32_e32 v144, v100
	v_exp_f32_e32 v145, v101
	v_exp_f32_e32 v146, v102
	v_exp_f32_e32 v147, v103
	s_waitcnt lgkmcnt(1)
	v_mfma_f32_32x32x16_bf16 v[80:95], v[152:155], v[168:171], v[80:95]
	v_exp_f32_e32 v148, v104
	v_exp_f32_e32 v149, v105
	v_exp_f32_e32 v150, v106
	v_exp_f32_e32 v151, v107
	s_waitcnt lgkmcnt(0)
	v_mfma_f32_32x32x16_bf16 v[64:79], v[156:159], v[168:171], v[64:79]
	v_exp_f32_e32 v152, v108
	v_exp_f32_e32 v153, v109
	v_exp_f32_e32 v154, v110
	v_exp_f32_e32 v155, v111
	s_cmp_gt_i32 s27, 2
	s_cselect_b32 s34, -3, 2
	s_waitcnt vmcnt(3)
	ds_write_b128 v208, v[128:131]
	s_add_i32 s34, s34, s27
	v_add_u32_e32 v128, s29, v195
	s_add_i32 s29, s13, -2
	s_mulk_i32 s34, 0x2400
	s_min_u32 s29, s29, s12
	v_add_u32_e32 v15, s34, v208
	s_lshl_b32 s92, s29, 13
	s_waitcnt vmcnt(2)
	ds_write_b128 v15, v[10:13] offset:36864
	s_add_u32 vcc_lo, s100, s92
	s_addc_u32 vcc_hi, s101, 0
	global_load_dwordx4 v[10:13], v248, vcc
	s_lshl_b32 s92, s28, 7
	v_add_f32_e32 v1, v1, v14
	s_add_u32 vcc_lo, s98, s92
	s_addc_u32 vcc_hi, s99, 0
	global_load_dwordx4 v[112:115], v249, vcc
	ds_read_b128 v[240:243], v195 offset:27648
	ds_read_b128 v[244:247], v195 offset:32256
	ds_read_b128 v[96:99], v128 offset:41472
	ds_read_b128 v[100:103], v128 offset:36864
	ds_read_b128 v[104:107], v128 offset:36896
	ds_read_b128 v[108:111], v128 offset:41504
	ds_read_b128 v[116:119], v128 offset:36928
	ds_read_b128 v[120:123], v128 offset:41536
	ds_read_b128 v[124:127], v128 offset:36960
	ds_read_b128 v[128:131], v128 offset:41568
	s_add_i32 s34, s27, 1
	s_setprio 1
	v_cvt_pk_bf16_f32 v132, v160, v161
	v_cvt_pk_bf16_f32 v133, v162, v163
	v_cvt_pk_bf16_f32 v134, v164, v165
	v_cvt_pk_bf16_f32 v135, v166, v167
	s_waitcnt lgkmcnt(6)
	s_nop 0
	v_mfma_f32_32x32x16_bf16 v[16:31], v[100:103], v[132:135], v[16:31]
	v_mov_b32_e32 v14, v160
	v_add_f32_e32 v14, v14, v161
	v_add_f32_e32 v14, v14, v162
	v_add_f32_e32 v14, v14, v163
	v_exp_f32_e32 v15, v80
	s_nop 0
	v_mfma_f32_32x32x16_bf16 v[32:47], v[96:99], v[132:135], v[32:47]
	v_cvt_pk_bf16_f32 v100, v184, v185
	v_cvt_pk_bf16_f32 v101, v186, v187
	v_cvt_pk_bf16_f32 v102, v136, v137
	v_cvt_pk_bf16_f32 v103, v138, v139
	v_add_f32_e32 v14, v14, v164
	v_add_f32_e32 v14, v14, v165
	v_add_f32_e32 v14, v14, v166
	v_add_f32_e32 v14, v14, v167
	s_waitcnt lgkmcnt(5)
	v_mfma_f32_32x32x16_bf16 v[16:31], v[104:107], v[100:103], v[16:31]
	v_add_f32_e32 v14, v14, v184
	v_add_f32_e32 v14, v14, v185
	v_add_f32_e32 v14, v14, v186
	v_add_f32_e32 v14, v14, v187
	v_exp_f32_e32 v184, v93
	v_exp_f32_e32 v185, v94
	s_waitcnt lgkmcnt(4)
	v_mfma_f32_32x32x16_bf16 v[32:47], v[108:111], v[100:103], v[32:47]
	v_cvt_pk_bf16_f32 v96, v140, v141
	v_cvt_pk_bf16_f32 v97, v142, v143
	v_cvt_pk_bf16_f32 v98, v144, v145
	v_cvt_pk_bf16_f32 v99, v146, v147
	v_add_f32_e32 v14, v14, v136
	v_add_f32_e32 v14, v14, v137
	v_add_f32_e32 v14, v14, v138
	v_add_f32_e32 v14, v14, v139
	s_waitcnt lgkmcnt(3)
	v_mfma_f32_32x32x16_bf16 v[16:31], v[116:119], v[96:99], v[16:31]
	v_add_f32_e32 v14, v14, v140
	v_add_f32_e32 v14, v14, v141
	v_add_f32_e32 v14, v14, v142
	v_add_f32_e32 v14, v14, v143
	v_exp_f32_e32 v186, v95
	s_waitcnt lgkmcnt(2)
	v_mfma_f32_32x32x16_bf16 v[32:47], v[120:123], v[96:99], v[32:47]
	v_cvt_pk_bf16_f32 v100, v148, v149
	v_cvt_pk_bf16_f32 v101, v150, v151
	v_cvt_pk_bf16_f32 v102, v152, v153
	v_cvt_pk_bf16_f32 v103, v154, v155
	v_add_f32_e32 v14, v14, v144
	v_add_f32_e32 v14, v14, v145
	v_add_f32_e32 v14, v14, v146
	v_add_f32_e32 v14, v14, v147
	s_waitcnt lgkmcnt(1)
	v_mfma_f32_32x32x16_bf16 v[16:31], v[124:127], v[100:103], v[16:31]
	v_add_f32_e32 v14, v14, v148
	v_add_f32_e32 v14, v14, v149
	v_add_f32_e32 v14, v14, v150
	v_add_f32_e32 v14, v14, v151
	v_exp_f32_e32 v144, v81
	v_exp_f32_e32 v145, v82
	s_waitcnt lgkmcnt(0)
	v_mfma_f32_32x32x16_bf16 v[32:47], v[128:131], v[100:103], v[32:47]
	v_add_f32_e32 v14, v14, v152
	v_add_f32_e32 v14, v14, v153
	v_add_f32_e32 v14, v14, v154
	v_add_f32_e32 v14, v14, v155
	v_exp_f32_e32 v146, v83
	v_exp_f32_e32 v147, v84
	s_setprio 0
	ds_read_b128 v[116:119], v195 offset:27680
	ds_read_b128 v[124:127], v195 offset:32288
	ds_read_b128 v[128:131], v195 offset:27712
	ds_read_b128 v[132:135], v195 offset:27744
	ds_read_b128 v[136:139], v195 offset:32320
	ds_read_b128 v[140:143], v195 offset:32352
	s_cmp_lg_u32 s27, 4
	s_cselect_b32 s27, s34, 0
	s_waitcnt lgkmcnt(6)
	v_mfma_f32_32x32x16_bf16 v[152:167], v[240:243], v[180:183], v[48:63]
	s_waitcnt lgkmcnt(5)
	v_mfma_f32_32x32x16_bf16 v[96:111], v[244:247], v[180:183], v[48:63]
	v_exp_f32_e32 v148, v85
	v_exp_f32_e32 v149, v86
	v_exp_f32_e32 v150, v87
	v_mfma_f32_32x32x16_bf16 v[152:167], v[116:119], v[176:179], v[152:167]
	v_exp_f32_e32 v120, v88
	v_exp_f32_e32 v121, v89
	v_exp_f32_e32 v122, v90
	v_exp_f32_e32 v123, v91
	s_waitcnt lgkmcnt(4)
	v_mfma_f32_32x32x16_bf16 v[96:111], v[124:127], v[176:179], v[96:111]
	v_exp_f32_e32 v151, v92
	s_waitcnt lgkmcnt(3)
	v_mfma_f32_32x32x16_bf16 v[152:167], v[128:131], v[172:175], v[152:167]
	v_exp_f32_e32 v124, v64
	v_exp_f32_e32 v125, v65
	v_exp_f32_e32 v126, v66
	v_exp_f32_e32 v127, v67
	s_waitcnt lgkmcnt(1)
	v_mfma_f32_32x32x16_bf16 v[96:111], v[136:139], v[172:175], v[96:111]
	v_exp_f32_e32 v128, v68
	v_exp_f32_e32 v129, v69
	v_exp_f32_e32 v130, v70
	v_exp_f32_e32 v131, v71
	v_mfma_f32_32x32x16_bf16 v[152:167], v[132:135], v[168:171], v[152:167]
	v_exp_f32_e32 v136, v72
	v_exp_f32_e32 v137, v73
	v_exp_f32_e32 v138, v74
	v_exp_f32_e32 v139, v75
	s_waitcnt lgkmcnt(0)
	v_mfma_f32_32x32x16_bf16 v[96:111], v[140:143], v[168:171], v[96:111]
	v_exp_f32_e32 v132, v76
	v_exp_f32_e32 v133, v77
	v_exp_f32_e32 v134, v78
	v_exp_f32_e32 v135, v79
	s_cmp_gt_i32 s27, 2
	s_cselect_b32 s28, -3, 2
	s_add_i32 s28, s28, s27
	s_mulk_i32 s28, 0x2400
	s_waitcnt vmcnt(3)
	ds_write_b128 v208, v[6:9] offset:9216
	v_add_u32_e32 v6, s28, v208
	s_add_i32 s28, s27, 1
	s_cmp_lg_u32 s27, 4
	s_cselect_b32 s27, s28, 0
	s_add_i32 s28, s13, -1
	s_min_u32 s28, s28, s12
	s_lshl_b32 s92, s28, 13
	s_waitcnt vmcnt(2)
	ds_write_b128 v6, v[2:5] offset:36864
	s_add_u32 vcc_lo, s100, s92
	s_addc_u32 vcc_hi, s101, 0
	global_load_dwordx4 v[6:9], v248, vcc
	s_lshl_b32 s92, s29, 7
	s_add_u32 vcc_lo, s98, s92
	s_addc_u32 vcc_hi, s99, 0
	global_load_dwordx4 v[2:5], v249, vcc
	s_nop 0
	s_mul_i32 s29, s27, 0x2400
	s_add_i32 s34, s29, 0xffffdc00
	s_cmp_lg_u32 s27, 0
	s_cselect_b32 s34, s34, 0x9000
	v_add_u32_e32 v92, s34, v195
	ds_read_b128 v[64:67], v92 offset:36864
	ds_read_b128 v[68:71], v92 offset:36896
	ds_read_b128 v[72:75], v92 offset:41472
	ds_read_b128 v[76:79], v92 offset:41504
	ds_read_b128 v[80:83], v92 offset:36928
	ds_read_b128 v[84:87], v92 offset:36960
	ds_read_b128 v[88:91], v92 offset:41536
	ds_read_b128 v[92:95], v92 offset:41568
	s_setprio 3
	v_cvt_pk_bf16_f32 v116, v15, v144
	v_cvt_pk_bf16_f32 v117, v145, v146
	v_cvt_pk_bf16_f32 v118, v147, v148
	v_cvt_pk_bf16_f32 v119, v149, v150
	s_waitcnt lgkmcnt(7)
	s_nop 0
	v_mfma_f32_32x32x16_bf16 v[16:31], v[64:67], v[116:119], v[16:31]
	v_mov_b32_e32 v187, v15
	v_add_f32_e32 v187, v187, v144
	v_add_f32_e32 v187, v187, v145
	v_add_f32_e32 v187, v187, v146
	v_exp_f32_e32 v15, v153
	v_exp_f32_e32 v210, v161
	s_waitcnt lgkmcnt(5)
	v_mfma_f32_32x32x16_bf16 v[32:47], v[72:75], v[116:119], v[32:47]
	v_cvt_pk_bf16_f32 v64, v120, v121
	v_cvt_pk_bf16_f32 v65, v122, v123
	v_cvt_pk_bf16_f32 v66, v151, v184
	v_cvt_pk_bf16_f32 v67, v185, v186
	v_add_f32_e32 v187, v187, v147
	v_add_f32_e32 v187, v187, v148
	v_add_f32_e32 v187, v187, v149
	v_add_f32_e32 v187, v187, v150
	s_nop 0
	v_mfma_f32_32x32x16_bf16 v[16:31], v[68:71], v[64:67], v[16:31]
	v_add_f32_e32 v187, v187, v120
	v_add_f32_e32 v187, v187, v121
	v_add_f32_e32 v187, v187, v122
	v_add_f32_e32 v187, v187, v123
	v_exp_f32_e32 v116, v154
	v_exp_f32_e32 v117, v155
	s_waitcnt lgkmcnt(4)
	v_mfma_f32_32x32x16_bf16 v[32:47], v[76:79], v[64:67], v[32:47]
	v_cvt_pk_bf16_f32 v68, v124, v125
	v_cvt_pk_bf16_f32 v69, v126, v127
	v_cvt_pk_bf16_f32 v70, v128, v129
	v_cvt_pk_bf16_f32 v71, v130, v131
	v_add_f32_e32 v187, v187, v151
	v_add_f32_e32 v187, v187, v184
	v_add_f32_e32 v187, v187, v185
	v_add_f32_e32 v187, v187, v186
	s_waitcnt lgkmcnt(3)
	v_mfma_f32_32x32x16_bf16 v[16:31], v[80:83], v[68:71], v[16:31]
	v_add_f32_e32 v187, v187, v124
	v_add_f32_e32 v187, v187, v125
	v_add_f32_e32 v187, v187, v126
	v_add_f32_e32 v187, v187, v127
	v_exp_f32_e32 v118, v156
	v_exp_f32_e32 v119, v157
	s_waitcnt lgkmcnt(1)
	v_mfma_f32_32x32x16_bf16 v[32:47], v[88:91], v[68:71], v[32:47]
	v_cvt_pk_bf16_f32 v64, v136, v137
	v_cvt_pk_bf16_f32 v65, v138, v139
	v_cvt_pk_bf16_f32 v66, v132, v133
	v_cvt_pk_bf16_f32 v67, v134, v135
	v_add_f32_e32 v187, v187, v128
	v_add_f32_e32 v187, v187, v129
	v_add_f32_e32 v187, v187, v130
	v_add_f32_e32 v187, v187, v131
	s_nop 0
	v_mfma_f32_32x32x16_bf16 v[16:31], v[84:87], v[64:67], v[16:31]
	v_add_f32_e32 v187, v187, v136
	v_add_f32_e32 v187, v187, v137
	v_add_f32_e32 v187, v187, v138
	v_add_f32_e32 v187, v187, v139
	v_exp_f32_e32 v184, v158
	v_exp_f32_e32 v185, v159
	s_waitcnt lgkmcnt(0)
	v_mfma_f32_32x32x16_bf16 v[32:47], v[92:95], v[64:67], v[32:47]
	v_add_f32_e32 v187, v187, v132
	v_add_f32_e32 v187, v187, v133
	v_add_f32_e32 v187, v187, v134
	v_add_f32_e32 v187, v187, v135
	s_setprio 2
	s_waitcnt lgkmcnt(0)
	s_barrier
	ds_read_b128 v[240:243], v195
	ds_read_b128 v[244:247], v195 offset:4608
	ds_read_b128 v[72:75], v195 offset:32
	ds_read_b128 v[76:79], v195 offset:4640
	ds_read_b128 v[80:83], v195 offset:64
	ds_read_b128 v[84:87], v195 offset:4672
	ds_read_b128 v[88:91], v195 offset:96
	ds_read_b128 v[92:95], v195 offset:4704
	v_add_f32_e32 v1, v1, v14
	s_waitcnt lgkmcnt(6)
	v_mfma_f32_32x32x16_bf16 v[136:151], v[240:243], v[180:183], v[48:63]
	v_exp_f32_e32 v14, v152
	v_mfma_f32_32x32x16_bf16 v[120:135], v[244:247], v[180:183], v[48:63]
	s_waitcnt lgkmcnt(5)
	v_mfma_f32_32x32x16_bf16 v[136:151], v[72:75], v[176:179], v[136:151]
	v_exp_f32_e32 v186, v160
	v_exp_f32_e32 v211, v162
	v_exp_f32_e32 v212, v163
	s_waitcnt lgkmcnt(4)
	v_mfma_f32_32x32x16_bf16 v[120:135], v[76:79], v[176:179], v[120:135]
	v_exp_f32_e32 v160, v164
	v_exp_f32_e32 v161, v165
	v_exp_f32_e32 v162, v166
	v_exp_f32_e32 v163, v167
	s_waitcnt lgkmcnt(3)
	v_mfma_f32_32x32x16_bf16 v[136:151], v[80:83], v[172:175], v[136:151]
	v_exp_f32_e32 v164, v96
	v_exp_f32_e32 v165, v97
	v_exp_f32_e32 v166, v98
	v_exp_f32_e32 v167, v99
	s_waitcnt lgkmcnt(2)
	v_mfma_f32_32x32x16_bf16 v[120:135], v[84:87], v[172:175], v[120:135]
	v_exp_f32_e32 v96, v100
	v_exp_f32_e32 v97, v101
	v_exp_f32_e32 v98, v102
	v_exp_f32_e32 v99, v103
	s_waitcnt lgkmcnt(1)
	v_mfma_f32_32x32x16_bf16 v[136:151], v[88:91], v[168:171], v[136:151]
	v_exp_f32_e32 v100, v104
	v_exp_f32_e32 v101, v105
	v_exp_f32_e32 v102, v106
	v_exp_f32_e32 v103, v107
	s_waitcnt lgkmcnt(0)
	v_mfma_f32_32x32x16_bf16 v[120:135], v[92:95], v[168:171], v[120:135]
	v_exp_f32_e32 v104, v108
	v_exp_f32_e32 v105, v109
	v_exp_f32_e32 v106, v110
	v_exp_f32_e32 v107, v111
	s_cmp_gt_i32 s27, 2
	s_cselect_b32 s34, -3, 2
	s_add_i32 s34, s34, s27
	s_mulk_i32 s34, 0x2400
	v_add_u32_e32 v88, s29, v195
	s_min_u32 s29, s13, s12
	s_waitcnt vmcnt(3)
	ds_write_b128 v208, v[10:13] offset:18432
	v_add_u32_e32 v10, s34, v208
	s_lshl_b32 s92, s29, 13
	s_waitcnt vmcnt(2)
	ds_write_b128 v10, v[112:115] offset:36864
	s_add_u32 vcc_lo, s100, s92
	s_addc_u32 vcc_hi, s101, 0
	global_load_dwordx4 v[152:155], v248, vcc
	s_lshl_b32 s92, s28, 7
	s_add_u32 vcc_lo, s98, s92
	s_addc_u32 vcc_hi, s99, 0
	global_load_dwordx4 v[156:159], v249, vcc
	ds_read_b128 v[240:243], v195 offset:9216
	ds_read_b128 v[244:247], v195 offset:13824
	ds_read_b128 v[10:13], v88 offset:41472
	ds_read_b128 v[64:67], v88 offset:36864
	ds_read_b128 v[68:71], v88 offset:36896
	ds_read_b128 v[72:75], v88 offset:41504
	ds_read_b128 v[76:79], v88 offset:36928
	ds_read_b128 v[80:83], v88 offset:41536
	ds_read_b128 v[84:87], v88 offset:36960
	ds_read_b128 v[88:91], v88 offset:41568
	v_add_f32_e32 v1, v1, v187
	s_setprio 1
	v_mov_b32_e32 v109, v136
	v_cvt_pk_bf16_f32 v92, v14, v15
	v_cvt_pk_bf16_f32 v93, v116, v117
	v_cvt_pk_bf16_f32 v94, v118, v119
	v_cvt_pk_bf16_f32 v95, v184, v185
	s_waitcnt lgkmcnt(6)
	s_nop 0
	v_mfma_f32_32x32x16_bf16 v[16:31], v[64:67], v[92:95], v[16:31]
	v_max3_f32 v109, v109, v137, v138
	v_max3_f32 v109, v109, v139, v140
	v_mov_b32_e32 v108, v14
	v_add_f32_e32 v108, v108, v15
	v_add_f32_e32 v108, v108, v116
	v_add_f32_e32 v108, v108, v117
	s_nop 0
	v_mfma_f32_32x32x16_bf16 v[32:47], v[10:13], v[92:95], v[32:47]
	v_cvt_pk_bf16_f32 v64, v186, v210
	v_cvt_pk_bf16_f32 v65, v211, v212
	v_cvt_pk_bf16_f32 v66, v160, v161
	v_cvt_pk_bf16_f32 v67, v162, v163
	v_max3_f32 v109, v109, v141, v142
	v_max3_f32 v109, v109, v143, v144
	v_add_f32_e32 v108, v108, v118
	v_add_f32_e32 v108, v108, v119
	v_add_f32_e32 v108, v108, v184
	v_add_f32_e32 v108, v108, v185
	s_waitcnt lgkmcnt(5)
	v_mfma_f32_32x32x16_bf16 v[16:31], v[68:71], v[64:67], v[16:31]
	v_max3_f32 v109, v109, v145, v146
	v_max3_f32 v109, v109, v147, v148
	v_add_f32_e32 v108, v108, v186
	v_add_f32_e32 v108, v108, v210
	v_add_f32_e32 v108, v108, v211
	v_add_f32_e32 v108, v108, v212
	s_waitcnt lgkmcnt(4)
	v_mfma_f32_32x32x16_bf16 v[32:47], v[72:75], v[64:67], v[32:47]
	v_cvt_pk_bf16_f32 v10, v164, v165
	v_cvt_pk_bf16_f32 v11, v166, v167
	v_cvt_pk_bf16_f32 v12, v96, v97
	v_cvt_pk_bf16_f32 v13, v98, v99
	v_max3_f32 v109, v109, v149, v150
	v_max3_f32 v109, v109, v151, v120
	v_add_f32_e32 v108, v108, v160
	v_add_f32_e32 v108, v108, v161
	v_add_f32_e32 v108, v108, v162
	v_add_f32_e32 v108, v108, v163
	s_waitcnt lgkmcnt(3)
	v_mfma_f32_32x32x16_bf16 v[16:31], v[76:79], v[10:13], v[16:31]
	v_max3_f32 v109, v109, v121, v122
	v_max3_f32 v109, v109, v123, v124
	v_add_f32_e32 v108, v108, v164
	v_add_f32_e32 v108, v108, v165
	v_add_f32_e32 v108, v108, v166
	v_add_f32_e32 v108, v108, v167
	s_waitcnt lgkmcnt(2)
	v_mfma_f32_32x32x16_bf16 v[32:47], v[80:83], v[10:13], v[32:47]
	v_cvt_pk_bf16_f32 v64, v100, v101
	v_cvt_pk_bf16_f32 v65, v102, v103
	v_cvt_pk_bf16_f32 v66, v104, v105
	v_cvt_pk_bf16_f32 v67, v106, v107
	v_max3_f32 v109, v109, v125, v126
	v_max3_f32 v109, v109, v127, v128
	v_add_f32_e32 v108, v108, v96
	v_add_f32_e32 v108, v108, v97
	v_add_f32_e32 v108, v108, v98
	v_add_f32_e32 v108, v108, v99
	s_waitcnt lgkmcnt(1)
	v_mfma_f32_32x32x16_bf16 v[16:31], v[84:87], v[64:67], v[16:31]
	v_max3_f32 v109, v109, v129, v130
	v_max3_f32 v109, v109, v131, v132
	v_add_f32_e32 v108, v108, v100
	v_add_f32_e32 v108, v108, v101
	v_add_f32_e32 v108, v108, v102
	v_add_f32_e32 v108, v108, v103
	s_waitcnt lgkmcnt(0)
	v_mfma_f32_32x32x16_bf16 v[32:47], v[88:91], v[64:67], v[32:47]
	v_max3_f32 v109, v109, v133, v134
	v_max3_f32 v109, v109, v135, v135
	v_add_f32_e32 v108, v108, v104
	v_add_f32_e32 v108, v108, v105
	v_add_f32_e32 v108, v108, v106
	v_add_f32_e32 v108, v108, v107
	s_setprio 0
	ds_read_b128 v[164:167], v195 offset:9248
	ds_read_b128 v[160:163], v195 offset:13856
	ds_read_b128 v[74:77], v195 offset:9280
	ds_read_b128 v[66:69], v195 offset:9312
	ds_read_b128 v[70:73], v195 offset:13888
	ds_read_b128 v[10:13], v195 offset:13920
	v_add_f32_e32 v64, v1, v108
	v_mov_b32_e32 v1, v109
	s_nop 1
	v_permlane32_swap_b32_e32 v109, v1
	v_max_f32_e32 v1, v1, v1
	v_max_f32_e32 v14, v109, v109
	v_max_f32_e32 v1, v14, v1
	v_cmp_lt_f32_e32 vcc, s52, v1
	s_cbranch_vccz .LBB0_663
	v_max_f32_e32 v1, v1, v1
	v_max_f32_e32 v14, 0, v1
	v_add_f32_e32 v209, v209, v14
	v_xor_b32_e32 v48, 0x80000000, v209
	v_pk_add_f32 v[136:137], v[136:137], v[14:15] op_sel_hi:[1,0] neg_lo:[0,1] neg_hi:[0,1]
	v_pk_add_f32 v[120:121], v[120:121], v[14:15] op_sel_hi:[1,0] neg_lo:[0,1] neg_hi:[0,1]
	v_pk_add_f32 v[138:139], v[138:139], v[14:15] op_sel_hi:[1,0] neg_lo:[0,1] neg_hi:[0,1]
	v_pk_add_f32 v[122:123], v[122:123], v[14:15] op_sel_hi:[1,0] neg_lo:[0,1] neg_hi:[0,1]
	v_pk_add_f32 v[140:141], v[140:141], v[14:15] op_sel_hi:[1,0] neg_lo:[0,1] neg_hi:[0,1]
	v_pk_add_f32 v[124:125], v[124:125], v[14:15] op_sel_hi:[1,0] neg_lo:[0,1] neg_hi:[0,1]
	v_pk_add_f32 v[142:143], v[142:143], v[14:15] op_sel_hi:[1,0] neg_lo:[0,1] neg_hi:[0,1]
	v_pk_add_f32 v[126:127], v[126:127], v[14:15] op_sel_hi:[1,0] neg_lo:[0,1] neg_hi:[0,1]
	v_pk_add_f32 v[144:145], v[144:145], v[14:15] op_sel_hi:[1,0] neg_lo:[0,1] neg_hi:[0,1]
	v_pk_add_f32 v[128:129], v[128:129], v[14:15] op_sel_hi:[1,0] neg_lo:[0,1] neg_hi:[0,1]
	v_pk_add_f32 v[146:147], v[146:147], v[14:15] op_sel_hi:[1,0] neg_lo:[0,1] neg_hi:[0,1]
	v_pk_add_f32 v[130:131], v[130:131], v[14:15] op_sel_hi:[1,0] neg_lo:[0,1] neg_hi:[0,1]
	v_pk_add_f32 v[148:149], v[148:149], v[14:15] op_sel_hi:[1,0] neg_lo:[0,1] neg_hi:[0,1]
	v_pk_add_f32 v[132:133], v[132:133], v[14:15] op_sel_hi:[1,0] neg_lo:[0,1] neg_hi:[0,1]
	v_pk_add_f32 v[150:151], v[150:151], v[14:15] op_sel_hi:[1,0] neg_lo:[0,1] neg_hi:[0,1]
	v_pk_add_f32 v[134:135], v[134:135], v[14:15] op_sel_hi:[1,0] neg_lo:[0,1] neg_hi:[0,1]
	v_exp_f32_e64 v14, -v14
	v_mov_b32_e32 v49, v48
	v_mov_b32_e32 v50, v48
	v_mov_b32_e32 v51, v48
	v_mov_b32_e32 v52, v48
	v_mov_b32_e32 v53, v48
	v_mov_b32_e32 v54, v48
	v_mov_b32_e32 v55, v48
	v_mov_b32_e32 v56, v48
	v_mov_b32_e32 v57, v48
	v_mov_b32_e32 v58, v48
	v_mov_b32_e32 v59, v48
	v_mov_b32_e32 v60, v48
	v_mov_b32_e32 v61, v48
	v_mov_b32_e32 v62, v48
	v_mov_b32_e32 v63, v48
	s_nop 11
	v_pk_mul_f32 v[30:31], v[30:31], v[14:15] op_sel_hi:[1,0]
	v_pk_mul_f32 v[28:29], v[28:29], v[14:15] op_sel_hi:[1,0]
	v_pk_mul_f32 v[26:27], v[26:27], v[14:15] op_sel_hi:[1,0]
	v_pk_mul_f32 v[24:25], v[24:25], v[14:15] op_sel_hi:[1,0]
	v_pk_mul_f32 v[22:23], v[22:23], v[14:15] op_sel_hi:[1,0]
	v_pk_mul_f32 v[20:21], v[20:21], v[14:15] op_sel_hi:[1,0]
	v_pk_mul_f32 v[18:19], v[18:19], v[14:15] op_sel_hi:[1,0]
	v_pk_mul_f32 v[16:17], v[16:17], v[14:15] op_sel_hi:[1,0]
	v_pk_mul_f32 v[46:47], v[46:47], v[14:15] op_sel_hi:[1,0]
	v_pk_mul_f32 v[44:45], v[44:45], v[14:15] op_sel_hi:[1,0]
	v_pk_mul_f32 v[42:43], v[42:43], v[14:15] op_sel_hi:[1,0]
	v_pk_mul_f32 v[40:41], v[40:41], v[14:15] op_sel_hi:[1,0]
	v_pk_mul_f32 v[38:39], v[38:39], v[14:15] op_sel_hi:[1,0]
	v_pk_mul_f32 v[36:37], v[36:37], v[14:15] op_sel_hi:[1,0]
	v_pk_mul_f32 v[34:35], v[34:35], v[14:15] op_sel_hi:[1,0]
	v_pk_mul_f32 v[32:33], v[32:33], v[14:15] op_sel_hi:[1,0]
	v_mul_f32_e32 v64, v64, v14
